# cache-policy split on the weight-conversion items: f32 reads stay non-temporal, bf16 weight stores back to the default policy
# baseline (speedup 1.0000x reference)
; __device__ __forceinline__ void tr_item(const float* __restrict__ W, int ldw, int k0, int n0, bf16* __restrict__ WT, int ldt, int drow, const float* __restrict__ mu, LAS float* scr, int lane, const float* __restrict__ gs = nullptr) {
; #pragma unroll 8
;     for (int i = 0; i < 32; ++i) { const int kk = 2 * i + (lane >> 5); scr[kk * 33 + (lane & 31)] = W[(size_t)(k0 + kk) * ldw + n0 + (lane & 31)]; }
;     asm volatile("s_waitcnt lgkmcnt(0)" ::: "memory");
.LBB0_1426:
	s_lshl_b32 s10, s5, 1
	s_lshl_b32 s11, s8, 1
	v_or_b32_e32 v41, s11, v14
	s_add_i32 s12, s10, 4
	s_add_i32 s13, s11, 4
	s_add_i32 s15, s11, 8
	v_add_u32_e32 v0, s4, v41
	v_or_b32_e32 v42, s12, v15
	v_or_b32_e32 v43, s13, v14
	v_mov_b32_e32 v7, v1
	v_or_b32_e32 v40, s10, v15
	s_add_i32 s17, s11, 12
	v_or_b32_e32 v45, s15, v14
	s_waitcnt lgkmcnt(3)
	v_lshlrev_b64 v[32:33], 12, v[0:1]
	v_add_u32_e32 v6, s7, v42
	v_add_u32_e32 v0, s4, v43
	v_mov_b32_e32 v5, v1
	s_add_i32 s14, s10, 8
	s_add_i32 s16, s10, 12
	s_add_i32 s19, s11, 16
	v_add_u32_e32 v4, s7, v40
	v_or_b32_e32 v47, s17, v14
	v_lshlrev_b64 v[6:7], 12, v[6:7]
	v_lshlrev_b64 v[34:35], 12, v[0:1]
	v_add_u32_e32 v0, s4, v45
	s_add_i32 s21, s11, 20
	v_or_b32_e32 v44, s14, v15
	v_or_b32_e32 v46, s16, v15
	v_or_b32_e32 v49, s19, v14
	v_lshlrev_b64 v[4:5], 12, v[4:5]
	v_lshl_add_u64 v[32:33], v[2:3], 0, v[32:33]
	v_lshl_add_u64 v[6:7], v[2:3], 0, v[6:7]
	v_lshlrev_b64 v[36:37], 12, v[0:1]
	v_add_u32_e32 v0, s4, v47
	v_mov_b32_e32 v9, v1
	v_mov_b32_e32 v11, v1
	s_add_i32 s18, s10, 16
	s_add_i32 s20, s10, 20
	s_add_i32 s23, s11, 24
	v_or_b32_e32 v51, s21, v14
	v_add_u32_e32 v8, s7, v44
	v_add_u32_e32 v10, s7, v46
	v_lshl_add_u64 v[4:5], v[2:3], 0, v[4:5]
	v_lshl_add_u64 v[34:35], v[2:3], 0, v[34:35]
	global_load_dword v56, v[32:33], off nt
	global_load_dword v57, v[4:5], off nt
	global_load_dword v58, v[34:35], off nt
	global_load_dword v59, v[6:7], off nt
	v_lshlrev_b64 v[6:7], 12, v[0:1]
	v_add_u32_e32 v0, s4, v49
	s_add_i32 s22, s10, 24
	s_add_i32 s10, s10, 28
	s_add_i32 s11, s11, 28
	v_or_b32_e32 v48, s18, v15
	v_or_b32_e32 v50, s20, v15
	v_or_b32_e32 v53, s23, v14
	v_lshlrev_b64 v[8:9], 12, v[8:9]
	v_lshlrev_b64 v[10:11], 12, v[10:11]
	v_lshl_add_u64 v[4:5], v[2:3], 0, v[36:37]
	v_lshl_add_u64 v[6:7], v[2:3], 0, v[6:7]
	v_lshlrev_b64 v[32:33], 12, v[0:1]
	v_add_u32_e32 v0, s4, v51
	s_waitcnt lgkmcnt(0)
	v_mov_b32_e32 v13, v1
	v_mov_b32_e32 v27, v1
	v_or_b32_e32 v52, s22, v15
	v_or_b32_e32 v54, s10, v15
	v_or_b32_e32 v55, s11, v14
	v_add_u32_e32 v12, s7, v48
	v_add_u32_e32 v26, s7, v50
	v_lshl_add_u64 v[8:9], v[2:3], 0, v[8:9]
	v_lshl_add_u64 v[10:11], v[2:3], 0, v[10:11]
	global_load_dword v60, v[4:5], off nt
	global_load_dword v61, v[8:9], off nt
	global_load_dword v62, v[6:7], off nt
	global_load_dword v63, v[10:11], off nt
	v_lshlrev_b64 v[6:7], 12, v[0:1]
	v_add_u32_e32 v0, s4, v53
	v_mov_b32_e32 v29, v1
	v_mov_b32_e32 v31, v1
	v_add_u32_e32 v28, s7, v52
	v_add_u32_e32 v30, s7, v54
	v_lshlrev_b64 v[12:13], 12, v[12:13]
	v_lshlrev_b64 v[26:27], 12, v[26:27]
	v_lshl_add_u64 v[4:5], v[2:3], 0, v[32:33]
	v_lshl_add_u64 v[6:7], v[2:3], 0, v[6:7]
	v_lshlrev_b64 v[8:9], 12, v[0:1]
	v_add_u32_e32 v0, s4, v55
	v_lshlrev_b64 v[28:29], 12, v[28:29]
	v_lshlrev_b64 v[30:31], 12, v[30:31]
	v_lshl_add_u64 v[12:13], v[2:3], 0, v[12:13]
	v_lshl_add_u64 v[26:27], v[2:3], 0, v[26:27]
	global_load_dword v64, v[4:5], off nt
	global_load_dword v65, v[12:13], off nt
	global_load_dword v66, v[6:7], off nt
	global_load_dword v67, v[26:27], off nt
	v_lshl_add_u64 v[4:5], v[2:3], 0, v[8:9]
	v_lshlrev_b64 v[6:7], 12, v[0:1]
	v_lshl_add_u64 v[28:29], v[2:3], 0, v[28:29]
	v_lshl_add_u64 v[30:31], v[2:3], 0, v[30:31]
	v_lshl_add_u64 v[6:7], v[2:3], 0, v[6:7]
	global_load_dword v0, v[4:5], off nt
	global_load_dword v68, v[28:29], off nt
	global_load_dword v69, v[6:7], off nt
	global_load_dword v70, v[30:31], off nt
	s_add_i32 s8, s8, 16
	s_add_i32 s5, s5, 16
	s_add_i32 s9, s9, -16
	v_mad_u64_u32 v[4:5], s[10:11], v41, s26, v[18:19]
	s_cmp_lg_u32 s9, 0
	v_mad_u64_u32 v[6:7], s[10:11], v40, s26, v[18:19]
	v_mad_u64_u32 v[8:9], s[10:11], v43, s26, v[18:19]
	v_mad_u64_u32 v[10:11], s[10:11], v42, s26, v[18:19]
	v_mad_u64_u32 v[12:13], s[10:11], v45, s26, v[18:19]
	v_mad_u64_u32 v[26:27], s[10:11], v44, s26, v[18:19]
	v_mad_u64_u32 v[28:29], s[10:11], v47, s26, v[18:19]
	v_mad_u64_u32 v[30:31], s[10:11], v46, s26, v[18:19]
	v_mad_u64_u32 v[32:33], s[10:11], v49, s26, v[18:19]
	v_mad_u64_u32 v[34:35], s[10:11], v48, s26, v[18:19]
	v_mad_u64_u32 v[36:37], s[10:11], v51, s26, v[18:19]
	v_mad_u64_u32 v[40:41], s[10:11], v50, s26, v[18:19]
	v_mad_u64_u32 v[42:43], s[10:11], v53, s26, v[18:19]
	v_mad_u64_u32 v[44:45], s[10:11], v52, s26, v[18:19]
	v_mad_u64_u32 v[46:47], s[10:11], v55, s26, v[18:19]
	v_mad_u64_u32 v[48:49], s[10:11], v54, s26, v[18:19]
	s_waitcnt vmcnt(15)
	ds_write_b32 v4, v56
	s_waitcnt vmcnt(14)
	ds_write_b32 v6, v57
	s_waitcnt vmcnt(13)
	ds_write_b32 v8, v58
	s_waitcnt vmcnt(12)
	ds_write_b32 v10, v59
	s_waitcnt vmcnt(11)
	ds_write_b32 v12, v60
	s_waitcnt vmcnt(10)
	ds_write_b32 v26, v61
	s_waitcnt vmcnt(9)
	ds_write_b32 v28, v62
	s_waitcnt vmcnt(8)
	ds_write_b32 v30, v63
	s_waitcnt vmcnt(7)
	ds_write_b32 v32, v64
	s_waitcnt vmcnt(6)
	ds_write_b32 v34, v65
	s_waitcnt vmcnt(5)
	ds_write_b32 v36, v66
	s_waitcnt vmcnt(4)
	ds_write_b32 v40, v67
	s_waitcnt vmcnt(3)
	ds_write_b32 v42, v0
	s_waitcnt vmcnt(2)
	ds_write_b32 v44, v68
	s_waitcnt vmcnt(1)
	ds_write_b32 v46, v69
	s_waitcnt vmcnt(0)
	ds_write_b32 v48, v70
	s_cbranch_scc1 .LBB0_1426
; #define LAS __attribute__((address_space(3)))
; __device__ __forceinline__ v4u pack8(const float (&f)[8]) { v4u w; w.x = cvt_pk_bf16(f[0], f[1]); w.y = cvt_pk_bf16(f[2], f[3]); w.z = cvt_pk_bf16(f[4], f[5]); w.w = cvt_pk_bf16(f[6], f[7]); return w; }
; __device__ __forceinline__ void tr_item(const float* __restrict__ W, int ldw, int k0, int n0, bf16* __restrict__ WT, int ldt, int drow, const float* __restrict__ mu, LAS float* scr, int lane, const float* __restrict__ gs = nullptr) {
;     ...
;     for (int j = 0; j < 4; ++j) {
;         const int n = (lane >> 3) + 8 * j; const LAS float* s = scr + (8 * c) * 33 + n;
;         float f[8];
; #pragma unroll
;         for (int e = 0; e < 8; ++e) f[e] = s[e * 33];
;         bf16* dp = WT + (size_t)(drow + n) * ldt + k0 + 8 * c;
;         if (mu) {
;             float f1[8], f2[8];
; #pragma unroll
;             for (int e = 0; e < 8; ++e) { f1[e] = f[e] * (1.f - mv[e]); f2[e] = f[e] * mv[e]; }
;             *(v4u*)dp = pack8(f1); *(v4u*)(dp + 1024) = pack8(f2);
;         } else { if (gs) {
; #pragma unroll
;             for (int e = 0; e < 8; ++e) f[e] *= mv[e]; }
;             *(v4u*)dp = pack8(f); }
;     }
	s_mul_i32 s1, s1, 0x580000
	v_readlane_b32 s5, v252, 10
	s_add_u32 s1, s5, s1
	v_readlane_b32 s5, v252, 11
	s_addc_u32 s5, s5, 0
	s_lshl_b32 s4, s4, 1
	s_add_u32 s4, s1, s4
	s_addc_u32 s5, s5, 0
	v_lshlrev_b32_e32 v0, 1, v20
	s_waitcnt lgkmcnt(0)
	v_lshl_add_u64 v[6:7], s[4:5], 0, v[0:1]
	v_or_b32_e32 v0, s0, v17
	v_mul_u32_u24_e32 v0, 0xb00, v0
	ds_read2_b32 v[8:9], v19 offset0:33 offset1:41
	ds_read2_b32 v[10:11], v19 offset1:8
	ds_read2_b32 v[12:13], v19 offset0:66 offset1:74
	ds_read2_b32 v[26:27], v19 offset0:99 offset1:107
	ds_read2_b32 v[28:29], v19 offset0:132 offset1:140
	ds_read2_b32 v[30:31], v19 offset0:165 offset1:173
	ds_read2_b32 v[32:33], v19 offset0:198 offset1:206
	ds_read2_b32 v[34:35], v19 offset0:231 offset1:239
	v_lshlrev_b32_e32 v0, 1, v0
	v_lshl_add_u64 v[36:37], v[6:7], 0, v[0:1]
	v_or_b32_e32 v0, s0, v21
	v_mul_u32_u24_e32 v0, 0xb00, v0
	v_lshlrev_b32_e32 v0, 1, v0
	s_waitcnt lgkmcnt(6)
	v_cvt_pk_bf16_f32 v2, v10, v8
	s_waitcnt lgkmcnt(4)
	v_cvt_pk_bf16_f32 v3, v12, v26
	s_waitcnt lgkmcnt(2)
	v_cvt_pk_bf16_f32 v4, v28, v30
	s_waitcnt lgkmcnt(0)
	v_cvt_pk_bf16_f32 v5, v32, v34
	global_store_dwordx4 v[36:37], v[2:5], off
	v_lshl_add_u64 v[36:37], v[6:7], 0, v[0:1]
	v_or_b32_e32 v0, s0, v38
	v_cvt_pk_bf16_f32 v2, v11, v9
	v_cvt_pk_bf16_f32 v3, v13, v27
	v_cvt_pk_bf16_f32 v4, v29, v31
	v_cvt_pk_bf16_f32 v5, v33, v35
	global_store_dwordx4 v[36:37], v[2:5], off
	v_mul_u32_u24_e32 v0, 0xb00, v0
	ds_read2_b32 v[8:9], v19 offset0:16 offset1:24
	ds_read2_b32 v[10:11], v19 offset0:49 offset1:57
	ds_read2_b32 v[12:13], v19 offset0:82 offset1:90
	ds_read2_b32 v[26:27], v19 offset0:115 offset1:123
	ds_read2_b32 v[28:29], v19 offset0:148 offset1:156
	ds_read2_b32 v[30:31], v19 offset0:181 offset1:189
	ds_read2_b32 v[32:33], v19 offset0:214 offset1:222
	ds_read2_b32 v[34:35], v19 offset0:247 offset1:255
	v_lshlrev_b32_e32 v0, 1, v0
	v_lshl_add_u64 v[36:37], v[6:7], 0, v[0:1]
	v_or_b32_e32 v0, s0, v39
	v_mul_u32_u24_e32 v0, 0xb00, v0
	v_lshlrev_b32_e32 v0, 1, v0
	s_waitcnt lgkmcnt(6)
	v_cvt_pk_bf16_f32 v2, v8, v10
	s_waitcnt lgkmcnt(4)
	v_cvt_pk_bf16_f32 v3, v12, v26
	s_waitcnt lgkmcnt(2)
	v_cvt_pk_bf16_f32 v4, v28, v30
	s_waitcnt lgkmcnt(0)
	v_cvt_pk_bf16_f32 v5, v32, v34
	v_lshl_add_u64 v[6:7], v[6:7], 0, v[0:1]
	global_store_dwordx4 v[36:37], v[2:5], off
	s_mov_b64 s[0:1], 0
	s_nop 0
	v_cvt_pk_bf16_f32 v2, v9, v11
	v_cvt_pk_bf16_f32 v3, v13, v27
	v_cvt_pk_bf16_f32 v4, v29, v31
	v_cvt_pk_bf16_f32 v5, v33, v35
	global_store_dwordx4 v[6:7], v[2:5], off
	s_waitcnt lgkmcnt(0)

; __device__ __forceinline__ void tr_item(const float* __restrict__ W, int ldw, int k0, int n0, bf16* __restrict__ WT, int ldt, int drow, const float* __restrict__ mu, LAS float* scr, int lane, const float* __restrict__ gs = nullptr) {
; #pragma unroll 8
;     for (int i = 0; i < 32; ++i) { const int kk = 2 * i + (lane >> 5); scr[kk * 33 + (lane & 31)] = W[(size_t)(k0 + kk) * ldw + n0 + (lane & 31)]; }
;     asm volatile("s_waitcnt lgkmcnt(0)" ::: "memory");
.LBB0_1440:
	s_lshl_b32 s9, s4, 1
	s_lshl_b32 s10, s7, 1
	v_or_b32_e32 v41, s10, v14
	s_add_i32 s11, s9, 4
	s_add_i32 s12, s10, 4
	s_add_i32 s14, s10, 8
	v_add_u32_e32 v0, s1, v41
	v_or_b32_e32 v42, s11, v15
	v_or_b32_e32 v43, s12, v14
	v_mov_b32_e32 v7, v1
	v_or_b32_e32 v40, s9, v15
	s_add_i32 s16, s10, 12
	v_or_b32_e32 v45, s14, v14
	s_waitcnt lgkmcnt(3)
	v_lshlrev_b64 v[32:33], 12, v[0:1]
	v_add_u32_e32 v6, s5, v42
	v_add_u32_e32 v0, s1, v43
	v_mov_b32_e32 v5, v1
	s_add_i32 s13, s9, 8
	s_add_i32 s15, s9, 12
	s_add_i32 s18, s10, 16
	v_add_u32_e32 v4, s5, v40
	v_or_b32_e32 v47, s16, v14
	v_lshlrev_b64 v[6:7], 12, v[6:7]
	v_lshlrev_b64 v[34:35], 12, v[0:1]
	v_add_u32_e32 v0, s1, v45
	s_add_i32 s20, s10, 20
	v_or_b32_e32 v44, s13, v15
	v_or_b32_e32 v46, s15, v15
	v_or_b32_e32 v49, s18, v14
	v_lshlrev_b64 v[4:5], 12, v[4:5]
	v_lshl_add_u64 v[32:33], v[2:3], 0, v[32:33]
	v_lshl_add_u64 v[6:7], v[2:3], 0, v[6:7]
	v_lshlrev_b64 v[36:37], 12, v[0:1]
	v_add_u32_e32 v0, s1, v47
	v_mov_b32_e32 v9, v1
	v_mov_b32_e32 v11, v1
	s_add_i32 s17, s9, 16
	s_add_i32 s19, s9, 20
	s_add_i32 s22, s10, 24
	v_or_b32_e32 v51, s20, v14
	v_add_u32_e32 v8, s5, v44
	v_add_u32_e32 v10, s5, v46
	v_lshl_add_u64 v[4:5], v[2:3], 0, v[4:5]
	v_lshl_add_u64 v[34:35], v[2:3], 0, v[34:35]
	global_load_dword v56, v[32:33], off nt
	global_load_dword v57, v[4:5], off nt
	global_load_dword v58, v[34:35], off nt
	global_load_dword v59, v[6:7], off nt
	v_lshlrev_b64 v[6:7], 12, v[0:1]
	v_add_u32_e32 v0, s1, v49
	s_add_i32 s21, s9, 24
	s_add_i32 s9, s9, 28
	s_add_i32 s10, s10, 28
	v_or_b32_e32 v48, s17, v15
	v_or_b32_e32 v50, s19, v15
	v_or_b32_e32 v53, s22, v14
	v_lshlrev_b64 v[8:9], 12, v[8:9]
	v_lshlrev_b64 v[10:11], 12, v[10:11]
	v_lshl_add_u64 v[4:5], v[2:3], 0, v[36:37]
	v_lshl_add_u64 v[6:7], v[2:3], 0, v[6:7]
	v_lshlrev_b64 v[32:33], 12, v[0:1]
	v_add_u32_e32 v0, s1, v51
	s_waitcnt lgkmcnt(0)
	v_mov_b32_e32 v13, v1
	v_mov_b32_e32 v27, v1
	v_or_b32_e32 v52, s21, v15
	v_or_b32_e32 v54, s9, v15
	v_or_b32_e32 v55, s10, v14
	v_add_u32_e32 v12, s5, v48
	v_add_u32_e32 v26, s5, v50
	v_lshl_add_u64 v[8:9], v[2:3], 0, v[8:9]
	v_lshl_add_u64 v[10:11], v[2:3], 0, v[10:11]
	global_load_dword v60, v[4:5], off nt
	global_load_dword v61, v[8:9], off nt
	global_load_dword v62, v[6:7], off nt
	global_load_dword v63, v[10:11], off nt
	v_lshlrev_b64 v[6:7], 12, v[0:1]
	v_add_u32_e32 v0, s1, v53
	v_mov_b32_e32 v29, v1
	v_mov_b32_e32 v31, v1
	v_add_u32_e32 v28, s5, v52
	v_add_u32_e32 v30, s5, v54
	v_lshlrev_b64 v[12:13], 12, v[12:13]
	v_lshlrev_b64 v[26:27], 12, v[26:27]
	v_lshl_add_u64 v[4:5], v[2:3], 0, v[32:33]
	v_lshl_add_u64 v[6:7], v[2:3], 0, v[6:7]
	v_lshlrev_b64 v[8:9], 12, v[0:1]
	v_add_u32_e32 v0, s1, v55
	v_lshlrev_b64 v[28:29], 12, v[28:29]
	v_lshlrev_b64 v[30:31], 12, v[30:31]
	v_lshl_add_u64 v[12:13], v[2:3], 0, v[12:13]
	v_lshl_add_u64 v[26:27], v[2:3], 0, v[26:27]
	global_load_dword v64, v[4:5], off nt
	global_load_dword v65, v[12:13], off nt
	global_load_dword v66, v[6:7], off nt
	global_load_dword v67, v[26:27], off nt
	v_lshl_add_u64 v[4:5], v[2:3], 0, v[8:9]
	v_lshlrev_b64 v[6:7], 12, v[0:1]
	v_lshl_add_u64 v[28:29], v[2:3], 0, v[28:29]
	v_lshl_add_u64 v[30:31], v[2:3], 0, v[30:31]
	v_lshl_add_u64 v[6:7], v[2:3], 0, v[6:7]
	global_load_dword v0, v[4:5], off nt
	global_load_dword v68, v[28:29], off nt
	global_load_dword v69, v[6:7], off nt
	global_load_dword v70, v[30:31], off nt
	s_add_i32 s7, s7, 16
	s_add_i32 s4, s4, 16
	s_add_i32 s8, s8, -16
	v_mad_u64_u32 v[4:5], s[10:11], v41, s26, v[18:19]
	s_cmp_lg_u32 s8, 0
	v_mad_u64_u32 v[6:7], s[10:11], v40, s26, v[18:19]
	v_mad_u64_u32 v[8:9], s[10:11], v43, s26, v[18:19]
	v_mad_u64_u32 v[10:11], s[10:11], v42, s26, v[18:19]
	v_mad_u64_u32 v[12:13], s[10:11], v45, s26, v[18:19]
	v_mad_u64_u32 v[26:27], s[10:11], v44, s26, v[18:19]
	v_mad_u64_u32 v[28:29], s[10:11], v47, s26, v[18:19]
	v_mad_u64_u32 v[30:31], s[10:11], v46, s26, v[18:19]
	v_mad_u64_u32 v[32:33], s[10:11], v49, s26, v[18:19]
	v_mad_u64_u32 v[34:35], s[10:11], v48, s26, v[18:19]
	v_mad_u64_u32 v[36:37], s[10:11], v51, s26, v[18:19]
	v_mad_u64_u32 v[40:41], s[10:11], v50, s26, v[18:19]
	v_mad_u64_u32 v[42:43], s[10:11], v53, s26, v[18:19]
	v_mad_u64_u32 v[44:45], s[10:11], v52, s26, v[18:19]
	v_mad_u64_u32 v[46:47], s[10:11], v55, s26, v[18:19]
	v_mad_u64_u32 v[48:49], s[10:11], v54, s26, v[18:19]
	s_waitcnt vmcnt(15)
	ds_write_b32 v4, v56
	s_waitcnt vmcnt(14)
	ds_write_b32 v6, v57
	s_waitcnt vmcnt(13)
	ds_write_b32 v8, v58
	s_waitcnt vmcnt(12)
	ds_write_b32 v10, v59
	s_waitcnt vmcnt(11)
	ds_write_b32 v12, v60
	s_waitcnt vmcnt(10)
	ds_write_b32 v26, v61
	s_waitcnt vmcnt(9)
	ds_write_b32 v28, v62
	s_waitcnt vmcnt(8)
	ds_write_b32 v30, v63
	s_waitcnt vmcnt(7)
	ds_write_b32 v32, v64
	s_waitcnt vmcnt(6)
	ds_write_b32 v34, v65
	s_waitcnt vmcnt(5)
	ds_write_b32 v36, v66
	s_waitcnt vmcnt(4)
	ds_write_b32 v40, v67
	s_waitcnt vmcnt(3)
	ds_write_b32 v42, v0
	s_waitcnt vmcnt(2)
	ds_write_b32 v44, v68
	s_waitcnt vmcnt(1)
	ds_write_b32 v46, v69
	s_waitcnt vmcnt(0)
	ds_write_b32 v48, v70
	s_cbranch_scc1 .LBB0_1440
; #define LAS __attribute__((address_space(3)))
; __device__ __forceinline__ v4u pack8(const float (&f)[8]) { v4u w; w.x = cvt_pk_bf16(f[0], f[1]); w.y = cvt_pk_bf16(f[2], f[3]); w.z = cvt_pk_bf16(f[4], f[5]); w.w = cvt_pk_bf16(f[6], f[7]); return w; }
; __device__ __forceinline__ void tr_item(const float* __restrict__ W, int ldw, int k0, int n0, bf16* __restrict__ WT, int ldt, int drow, const float* __restrict__ mu, LAS float* scr, int lane, const float* __restrict__ gs = nullptr) {
;     ...
;     for (int j = 0; j < 4; ++j) {
;         const int n = (lane >> 3) + 8 * j; const LAS float* s = scr + (8 * c) * 33 + n;
;         float f[8];
; #pragma unroll
;         for (int e = 0; e < 8; ++e) f[e] = s[e * 33];
;         bf16* dp = WT + (size_t)(drow + n) * ldt + k0 + 8 * c;
;         if (mu) {
;             float f1[8], f2[8];
; #pragma unroll
;             for (int e = 0; e < 8; ++e) { f1[e] = f[e] * (1.f - mv[e]); f2[e] = f[e] * mv[e]; }
;             *(v4u*)dp = pack8(f1); *(v4u*)(dp + 1024) = pack8(f2);
;         } else { if (gs) {
; #pragma unroll
;             for (int e = 0; e < 8; ++e) f[e] *= mv[e]; }
;             *(v4u*)dp = pack8(f); }
;     }
; __device__ __forceinline__ void ph_p0(const Params& p, LAS unsigned char* lds, int tid, int lane, int wave) {
;     ...
;         if (r < C_WO) { const int j = r / 512, q = r % 512, kb = q / 32, nb = q % 32;
;             tr_item(p.in[I_WO] + (size_t)j * D * D, D, 64 * kb, 32 * nb, (bf16*)(ws + WS_WO + j * SZ_WO), D, 32 * nb, nullptr, scr, lane); continue; }
	s_lshl_b64 s[4:5], s[94:95], 21
	v_readlane_b32 s7, v252, 14
	s_add_u32 s4, s7, s4
	v_readlane_b32 s7, v252, 15
	s_addc_u32 s5, s7, s5
	s_lshl_b32 s1, s1, 1
	s_waitcnt lgkmcnt(0)
	s_add_u32 s4, s4, s1
	s_addc_u32 s5, s5, 0
	v_lshlrev_b32_e32 v0, 1, v20
	ds_read2_b32 v[8:9], v19 offset0:33 offset1:41
	ds_read2_b32 v[10:11], v19 offset1:8
	ds_read2_b32 v[12:13], v19 offset0:66 offset1:74
	ds_read2_b32 v[26:27], v19 offset0:99 offset1:107
	ds_read2_b32 v[28:29], v19 offset0:132 offset1:140
	ds_read2_b32 v[30:31], v19 offset0:165 offset1:173
	ds_read2_b32 v[32:33], v19 offset0:198 offset1:206
	ds_read2_b32 v[34:35], v19 offset0:231 offset1:239
	v_lshl_add_u64 v[6:7], s[4:5], 0, v[0:1]
	v_or_b32_e32 v0, s0, v17
	v_lshlrev_b32_e32 v0, 11, v0
	v_lshl_add_u64 v[36:37], v[6:7], 0, v[0:1]
	v_or_b32_e32 v0, s0, v21
	v_lshlrev_b32_e32 v0, 11, v0
	s_waitcnt lgkmcnt(6)
	v_cvt_pk_bf16_f32 v2, v10, v8
	s_waitcnt lgkmcnt(4)
	v_cvt_pk_bf16_f32 v3, v12, v26
	s_waitcnt lgkmcnt(2)
	v_cvt_pk_bf16_f32 v4, v28, v30
	s_waitcnt lgkmcnt(0)
	v_cvt_pk_bf16_f32 v5, v32, v34
	global_store_dwordx4 v[36:37], v[2:5], off
	v_lshl_add_u64 v[36:37], v[6:7], 0, v[0:1]
	v_or_b32_e32 v0, s0, v38
	v_cvt_pk_bf16_f32 v2, v11, v9
	v_cvt_pk_bf16_f32 v3, v13, v27
	v_cvt_pk_bf16_f32 v4, v29, v31
	v_cvt_pk_bf16_f32 v5, v33, v35
	global_store_dwordx4 v[36:37], v[2:5], off
	ds_read2_b32 v[8:9], v19 offset0:16 offset1:24
	ds_read2_b32 v[10:11], v19 offset0:49 offset1:57
	ds_read2_b32 v[12:13], v19 offset0:82 offset1:90
	ds_read2_b32 v[26:27], v19 offset0:115 offset1:123
	ds_read2_b32 v[28:29], v19 offset0:148 offset1:156
	ds_read2_b32 v[30:31], v19 offset0:181 offset1:189
	ds_read2_b32 v[32:33], v19 offset0:214 offset1:222
	ds_read2_b32 v[34:35], v19 offset0:247 offset1:255
	v_lshlrev_b32_e32 v0, 11, v0
	v_lshl_add_u64 v[36:37], v[6:7], 0, v[0:1]
	v_or_b32_e32 v0, s0, v39
	v_lshlrev_b32_e32 v0, 11, v0
	s_waitcnt lgkmcnt(6)
	v_cvt_pk_bf16_f32 v2, v8, v10
	s_waitcnt lgkmcnt(4)
	v_cvt_pk_bf16_f32 v3, v12, v26
	s_waitcnt lgkmcnt(2)
	v_cvt_pk_bf16_f32 v4, v28, v30
	s_waitcnt lgkmcnt(0)
	v_cvt_pk_bf16_f32 v5, v32, v34
	v_lshl_add_u64 v[6:7], v[6:7], 0, v[0:1]
	global_store_dwordx4 v[36:37], v[2:5], off
	s_nop 1
	v_cvt_pk_bf16_f32 v2, v9, v11
	v_cvt_pk_bf16_f32 v3, v13, v27
	v_cvt_pk_bf16_f32 v4, v29, v31
	v_cvt_pk_bf16_f32 v5, v33, v35
	global_store_dwordx4 v[6:7], v[2:5], off
	s_waitcnt lgkmcnt(0)

; __device__ __forceinline__ void tr_item(const float* __restrict__ W, int ldw, int k0, int n0, bf16* __restrict__ WT, int ldt, int drow, const float* __restrict__ mu, LAS float* scr, int lane, const float* __restrict__ gs = nullptr) {
; #pragma unroll 8
;     for (int i = 0; i < 32; ++i) { const int kk = 2 * i + (lane >> 5); scr[kk * 33 + (lane & 31)] = W[(size_t)(k0 + kk) * ldw + n0 + (lane & 31)]; }
;     asm volatile("s_waitcnt lgkmcnt(0)" ::: "memory");
.LBB0_1445:
	s_lshl_b32 s8, s4, 1
	s_lshl_b32 s9, s5, 1
	v_or_b32_e32 v0, s8, v15
	v_or_b32_e32 v48, s9, v14
	s_add_i32 s10, s8, 4
	s_add_i32 s11, s9, 4
	s_add_i32 s12, s8, 8
	s_add_i32 s13, s9, 8
	s_add_i32 s14, s8, 12
	s_add_i32 s15, s9, 12
	s_add_i32 s16, s8, 16
	s_add_i32 s17, s9, 16
	s_add_i32 s18, s8, 20
	s_add_i32 s19, s9, 20
	s_add_i32 s20, s8, 24
	s_add_i32 s21, s9, 24
	s_add_i32 s8, s8, 28
	s_add_i32 s9, s9, 28
	v_add_u32_e32 v4, s0, v48
	v_or_b32_e32 v49, s10, v15
	v_or_b32_e32 v50, s11, v14
	v_or_b32_e32 v51, s12, v15
	v_or_b32_e32 v52, s13, v14
	v_or_b32_e32 v53, s14, v15
	v_or_b32_e32 v54, s15, v14
	v_or_b32_e32 v55, s16, v15
	v_or_b32_e32 v56, s17, v14
	v_or_b32_e32 v57, s18, v15
	v_or_b32_e32 v58, s19, v14
	v_or_b32_e32 v59, s20, v15
	v_or_b32_e32 v60, s21, v14
	v_or_b32_e32 v61, s8, v15
	v_or_b32_e32 v62, s9, v14
	v_add_u32_e32 v2, s1, v0
	v_ashrrev_i32_e32 v5, 31, v4
	v_add_u32_e32 v6, s1, v49
	v_add_u32_e32 v8, s0, v50
	v_add_u32_e32 v10, s1, v51
	s_waitcnt lgkmcnt(0)
	v_add_u32_e32 v12, s0, v52
	v_add_u32_e32 v26, s1, v53
	v_add_u32_e32 v28, s0, v54
	v_add_u32_e32 v30, s1, v55
	v_add_u32_e32 v32, s0, v56
	v_add_u32_e32 v34, s1, v57
	v_add_u32_e32 v36, s0, v58
	v_add_u32_e32 v40, s1, v59
	v_add_u32_e32 v42, s0, v60
	v_add_u32_e32 v44, s1, v61
	v_add_u32_e32 v46, s0, v62
	v_ashrrev_i32_e32 v3, 31, v2
	v_lshlrev_b64 v[4:5], 7, v[4:5]
	v_ashrrev_i32_e32 v9, 31, v8
	v_ashrrev_i32_e32 v7, 31, v6
	v_ashrrev_i32_e32 v13, 31, v12
	v_ashrrev_i32_e32 v11, 31, v10
	v_ashrrev_i32_e32 v29, 31, v28
	v_ashrrev_i32_e32 v27, 31, v26
	v_ashrrev_i32_e32 v33, 31, v32
	v_ashrrev_i32_e32 v31, 31, v30
	v_ashrrev_i32_e32 v37, 31, v36
	v_ashrrev_i32_e32 v35, 31, v34
	v_ashrrev_i32_e32 v43, 31, v42
	v_ashrrev_i32_e32 v41, 31, v40
	v_ashrrev_i32_e32 v47, 31, v46
	v_ashrrev_i32_e32 v45, 31, v44
	v_lshlrev_b64 v[2:3], 7, v[2:3]
	v_lshl_add_u64 v[4:5], v[24:25], 0, v[4:5]
	v_lshlrev_b64 v[6:7], 7, v[6:7]
	v_lshlrev_b64 v[8:9], 7, v[8:9]
	v_lshlrev_b64 v[10:11], 7, v[10:11]
	v_lshlrev_b64 v[12:13], 7, v[12:13]
	v_lshlrev_b64 v[26:27], 7, v[26:27]
	v_lshlrev_b64 v[28:29], 7, v[28:29]
	v_lshlrev_b64 v[30:31], 7, v[30:31]
	v_lshlrev_b64 v[32:33], 7, v[32:33]
	v_lshlrev_b64 v[34:35], 7, v[34:35]
	v_lshlrev_b64 v[36:37], 7, v[36:37]
	v_lshlrev_b64 v[40:41], 7, v[40:41]
	v_lshlrev_b64 v[42:43], 7, v[42:43]
	v_lshlrev_b64 v[44:45], 7, v[44:45]
	v_lshlrev_b64 v[46:47], 7, v[46:47]
	v_lshl_add_u64 v[2:3], v[24:25], 0, v[2:3]
	v_lshl_add_u64 v[8:9], v[24:25], 0, v[8:9]
	v_lshl_add_u64 v[6:7], v[24:25], 0, v[6:7]
	v_lshl_add_u64 v[12:13], v[24:25], 0, v[12:13]
	v_lshl_add_u64 v[10:11], v[24:25], 0, v[10:11]
	v_lshl_add_u64 v[28:29], v[24:25], 0, v[28:29]
	v_lshl_add_u64 v[26:27], v[24:25], 0, v[26:27]
	v_lshl_add_u64 v[32:33], v[24:25], 0, v[32:33]
	v_lshl_add_u64 v[30:31], v[24:25], 0, v[30:31]
	v_lshl_add_u64 v[36:37], v[24:25], 0, v[36:37]
	v_lshl_add_u64 v[34:35], v[24:25], 0, v[34:35]
	v_lshl_add_u64 v[42:43], v[24:25], 0, v[42:43]
	v_lshl_add_u64 v[40:41], v[24:25], 0, v[40:41]
	v_lshl_add_u64 v[46:47], v[24:25], 0, v[46:47]
	v_lshl_add_u64 v[44:45], v[24:25], 0, v[44:45]
	global_load_dword v63, v[4:5], off nt
	global_load_dword v64, v[2:3], off nt
	global_load_dword v65, v[8:9], off nt
	global_load_dword v66, v[6:7], off nt
	global_load_dword v67, v[12:13], off nt
	global_load_dword v68, v[10:11], off nt
	global_load_dword v69, v[28:29], off nt
	global_load_dword v70, v[26:27], off nt
	global_load_dword v71, v[32:33], off nt
	global_load_dword v72, v[30:31], off nt
	global_load_dword v73, v[36:37], off nt
	global_load_dword v74, v[34:35], off nt
	global_load_dword v75, v[42:43], off nt
	global_load_dword v76, v[40:41], off nt
	global_load_dword v77, v[46:47], off nt
	global_load_dword v78, v[44:45], off nt
	s_add_i32 s5, s5, 16
	s_add_i32 s4, s4, 16
	s_add_i32 s7, s7, -16
	v_mad_u64_u32 v[2:3], s[8:9], v48, s26, v[18:19]
	s_cmp_lg_u32 s7, 0
	v_mad_u64_u32 v[4:5], s[8:9], v0, s26, v[18:19]
	v_mad_u64_u32 v[6:7], s[8:9], v50, s26, v[18:19]
	v_mad_u64_u32 v[8:9], s[8:9], v49, s26, v[18:19]
	v_mad_u64_u32 v[10:11], s[8:9], v52, s26, v[18:19]
	v_mad_u64_u32 v[12:13], s[8:9], v51, s26, v[18:19]
	v_mad_u64_u32 v[26:27], s[8:9], v54, s26, v[18:19]
	v_mad_u64_u32 v[28:29], s[8:9], v53, s26, v[18:19]
	v_mad_u64_u32 v[30:31], s[8:9], v56, s26, v[18:19]
	v_mad_u64_u32 v[32:33], s[8:9], v55, s26, v[18:19]
	v_mad_u64_u32 v[34:35], s[8:9], v58, s26, v[18:19]
	v_mad_u64_u32 v[36:37], s[8:9], v57, s26, v[18:19]
	v_mad_u64_u32 v[40:41], s[8:9], v60, s26, v[18:19]
	v_mad_u64_u32 v[42:43], s[8:9], v59, s26, v[18:19]
	v_mad_u64_u32 v[44:45], s[8:9], v62, s26, v[18:19]
	v_mad_u64_u32 v[46:47], s[8:9], v61, s26, v[18:19]
	s_waitcnt vmcnt(15)
	ds_write_b32 v2, v63
	s_waitcnt vmcnt(14)
	ds_write_b32 v4, v64
	s_waitcnt vmcnt(13)
	ds_write_b32 v6, v65
	s_waitcnt vmcnt(12)
	ds_write_b32 v8, v66
	s_waitcnt vmcnt(11)
	ds_write_b32 v10, v67
	s_waitcnt vmcnt(10)
	ds_write_b32 v12, v68
	s_waitcnt vmcnt(9)
	ds_write_b32 v26, v69
	s_waitcnt vmcnt(8)
	ds_write_b32 v28, v70
	s_waitcnt vmcnt(7)
	ds_write_b32 v30, v71
	s_waitcnt vmcnt(6)
	ds_write_b32 v32, v72
	s_waitcnt vmcnt(5)
	ds_write_b32 v34, v73
	s_waitcnt vmcnt(4)
	ds_write_b32 v36, v74
	s_waitcnt vmcnt(3)
	ds_write_b32 v40, v75
	s_waitcnt vmcnt(2)
	ds_write_b32 v42, v76
	s_waitcnt vmcnt(1)
	ds_write_b32 v44, v77
	s_waitcnt vmcnt(0)
	ds_write_b32 v46, v78
	s_cbranch_scc1 .LBB0_1445
; #define LAS __attribute__((address_space(3)))
; __device__ __forceinline__ v4u pack8(const float (&f)[8]) { v4u w; w.x = cvt_pk_bf16(f[0], f[1]); w.y = cvt_pk_bf16(f[2], f[3]); w.z = cvt_pk_bf16(f[4], f[5]); w.w = cvt_pk_bf16(f[6], f[7]); return w; }
; __device__ __forceinline__ void tr_item(const float* __restrict__ W, int ldw, int k0, int n0, bf16* __restrict__ WT, int ldt, int drow, const float* __restrict__ mu, LAS float* scr, int lane, const float* __restrict__ gs = nullptr) {
;     ...
;     if (mu) {
; #pragma unroll
;         for (int e = 0; e < 8; ++e) mv[e] = mu[k0 + 8 * c + e];
;     } else if (gs) {
; #pragma unroll
;         for (int e = 0; e < 8; ++e) mv[e] = gs[k0 + 8 * c + e];
;     }
; #pragma unroll
;     for (int j = 0; j < 4; ++j) {
;         const int n = (lane >> 3) + 8 * j; const LAS float* s = scr + (8 * c) * 33 + n;
;         float f[8];
; #pragma unroll
;         for (int e = 0; e < 8; ++e) f[e] = s[e * 33];
;         bf16* dp = WT + (size_t)(drow + n) * ldt + k0 + 8 * c;
;         if (mu) {
;             float f1[8], f2[8];
; #pragma unroll
;             for (int e = 0; e < 8; ++e) { f1[e] = f[e] * (1.f - mv[e]); f2[e] = f[e] * mv[e]; }
;             *(v4u*)dp = pack8(f1); *(v4u*)(dp + 1024) = pack8(f2);
;         } else { if (gs) {
; #pragma unroll
;             for (int e = 0; e < 8; ++e) f[e] *= mv[e]; }
;             *(v4u*)dp = pack8(f); }
;     }
; __device__ __forceinline__ void ph_p0(const Params& p, LAS unsigned char* lds, int tid, int lane, int wave) {
;     ...
;         if (r < C_V1) { const int kb = r;
;             tr_item(p.in[I_V1], LV, 64 * kb, 0, (bf16*)(ws + WS_WRW + 1 * SZ_WRW), KRW, 3360, p.in[I_MU] + (size_t)(1 * 6 + 3) * D, scr, lane); continue; }
	v_readlane_b32 s4, v253, 14
	v_or_b32_e32 v0, s0, v20
	v_readlane_b32 s5, v253, 15
	s_waitcnt lgkmcnt(0)
	s_mov_b32 s1, s95
	v_lshl_add_u64 v[6:7], s[0:1], 1, v[22:23]
	v_lshl_add_u64 v[2:3], v[0:1], 2, s[4:5]
	global_load_dwordx4 v[8:11], v[2:3], off
	s_nop 0
	global_load_dwordx4 v[2:5], v[2:3], off offset:16
	ds_read2_b32 v[12:13], v19 offset0:33 offset1:41
	ds_read2_b32 v[30:31], v19 offset0:66 offset1:74
	ds_read2_b32 v[32:33], v19 offset0:99 offset1:107
	ds_read2_b32 v[34:35], v19 offset0:132 offset1:140
	ds_read2_b32 v[36:37], v19 offset0:165 offset1:173
	ds_read2_b32 v[40:41], v19 offset0:198 offset1:206
	ds_read2_b32 v[42:43], v19 offset0:231 offset1:239
	s_mov_b32 s0, 0xd20000
	ds_read2_b32 v[44:45], v19 offset1:8
	ds_read2_b32 v[46:47], v19 offset0:16 offset1:24
	ds_read2_b32 v[48:49], v19 offset0:49 offset1:57
	ds_read2_b32 v[50:51], v19 offset0:82 offset1:90
	v_add_co_u32_e32 v52, vcc, s0, v6
	s_mov_b32 s0, 0xd28000
	s_nop 0
	v_addc_co_u32_e32 v53, vcc, 0, v7, vcc
	v_add_co_u32_e32 v54, vcc, s0, v6
	s_mov_b32 s0, 0xd30000
	s_nop 0
	v_addc_co_u32_e32 v55, vcc, 0, v7, vcc
	s_waitcnt vmcnt(1) lgkmcnt(3)
	v_mul_f32_e32 v26, v8, v44
	v_mul_f32_e32 v27, v9, v12
	v_sub_f32_e32 v57, 1.0, v10
	v_mul_f32_e32 v28, v10, v30
	v_sub_f32_e32 v58, 1.0, v11
	v_mul_f32_e32 v29, v11, v32
	s_waitcnt vmcnt(0)
	v_mul_f32_e32 v60, v2, v34
	v_sub_f32_e32 v61, 1.0, v3
	v_mul_f32_e32 v62, v3, v36
	v_sub_f32_e32 v0, 1.0, v8
	v_sub_f32_e32 v56, 1.0, v9
	v_sub_f32_e32 v59, 1.0, v2
	v_sub_f32_e32 v63, 1.0, v4
	v_mul_f32_e32 v64, v4, v40
	v_sub_f32_e32 v65, 1.0, v5
	v_mul_f32_e32 v66, v5, v42
	v_mul_f32_e32 v67, v8, v45
	v_mul_f32_e32 v68, v9, v13
	v_mul_f32_e32 v69, v10, v31
	v_mul_f32_e32 v70, v11, v33
	v_mul_f32_e32 v71, v2, v35
	v_mul_f32_e32 v72, v3, v37
	v_mul_f32_e32 v73, v4, v41
	v_mul_f32_e32 v74, v5, v43
	v_mul_f32_e32 v75, v57, v30
	v_mul_f32_e32 v76, v58, v32
	v_mul_f32_e32 v36, v61, v36
	v_cvt_pk_bf16_f32 v26, v26, v27
	v_cvt_pk_bf16_f32 v27, v28, v29
	v_cvt_pk_bf16_f32 v28, v60, v62
	v_cvt_pk_bf16_f32 v29, v64, v66
	v_mul_f32_e32 v60, v57, v31
	v_mul_f32_e32 v62, v58, v33
	v_cvt_pk_bf16_f32 v30, v67, v68
	v_cvt_pk_bf16_f32 v31, v69, v70
	v_cvt_pk_bf16_f32 v32, v71, v72
	v_cvt_pk_bf16_f32 v33, v73, v74
	v_mul_f32_e32 v44, v0, v44
	v_mul_f32_e32 v12, v56, v12
	v_mul_f32_e32 v77, v59, v34
	v_mul_f32_e32 v40, v63, v40
	v_mul_f32_e32 v42, v65, v42
	v_mul_f32_e32 v45, v0, v45
	v_mul_f32_e32 v13, v56, v13
	v_mul_f32_e32 v64, v59, v35
	v_mul_f32_e32 v66, v61, v37
	v_mul_f32_e32 v41, v63, v41
	v_mul_f32_e32 v43, v65, v43
	v_cvt_pk_bf16_f32 v34, v44, v12
	v_cvt_pk_bf16_f32 v35, v75, v76
	v_cvt_pk_bf16_f32 v36, v77, v36
	v_cvt_pk_bf16_f32 v37, v40, v42
	global_store_dwordx4 v[52:53], v[26:29], off offset:2048
	s_waitcnt lgkmcnt(2)
	v_mul_f32_e32 v42, v8, v46
	s_waitcnt lgkmcnt(0)
	v_mul_f32_e32 v44, v10, v50
	v_cvt_pk_bf16_f32 v26, v45, v13
	v_cvt_pk_bf16_f32 v27, v60, v62
	v_cvt_pk_bf16_f32 v28, v64, v66
	v_cvt_pk_bf16_f32 v29, v41, v43
	global_store_dwordx4 v[54:55], v[30:33], off offset:2048
	global_store_dwordx4 v[52:53], v[34:37], off
	global_store_dwordx4 v[54:55], v[26:29], off
	ds_read2_b32 v[12:13], v19 offset0:115 offset1:123
	ds_read2_b32 v[30:31], v19 offset0:148 offset1:156
	ds_read2_b32 v[32:33], v19 offset0:181 offset1:189
	ds_read2_b32 v[34:35], v19 offset0:214 offset1:222
	ds_read2_b32 v[36:37], v19 offset0:247 offset1:255
	v_mul_f32_e32 v26, v0, v46
	v_mul_f32_e32 v27, v56, v48
	v_mul_f32_e32 v28, v57, v50
	s_waitcnt lgkmcnt(3)
	v_mul_f32_e32 v40, v59, v30
	v_mul_f32_e32 v29, v58, v12
	s_waitcnt lgkmcnt(2)
	v_mul_f32_e32 v41, v61, v32
	v_cvt_pk_bf16_f32 v26, v26, v27
	v_cvt_pk_bf16_f32 v27, v28, v29
	v_cvt_pk_bf16_f32 v28, v40, v41
	v_add_co_u32_e32 v40, vcc, s0, v6
	s_waitcnt lgkmcnt(1)
	v_mul_f32_e32 v45, v63, v34
	s_waitcnt lgkmcnt(0)
	v_mul_f32_e32 v46, v65, v36
	v_cvt_pk_bf16_f32 v29, v45, v46
	v_addc_co_u32_e32 v41, vcc, 0, v7, vcc
	v_mul_f32_e32 v43, v9, v48
	v_mul_f32_e32 v12, v11, v12
	v_mul_f32_e32 v30, v2, v30
	v_mul_f32_e32 v32, v3, v32
	v_mul_f32_e32 v34, v4, v34
	v_mul_f32_e32 v36, v5, v36
	global_store_dwordx4 v[40:41], v[26:29], off
	v_add_co_u32_e32 v6, vcc, 0xd38000, v6
	s_nop 0
	v_cvt_pk_bf16_f32 v26, v42, v43
	v_cvt_pk_bf16_f32 v27, v44, v12
	v_cvt_pk_bf16_f32 v28, v30, v32
	v_cvt_pk_bf16_f32 v29, v34, v36
	global_store_dwordx4 v[40:41], v[26:29], off offset:2048
	v_mul_f32_e32 v0, v0, v47
	v_mul_f32_e32 v12, v56, v49
	v_mul_f32_e32 v26, v57, v51
	v_mul_f32_e32 v27, v58, v13
	v_mul_f32_e32 v11, v11, v13
	v_mul_f32_e32 v13, v59, v31
	v_mul_f32_e32 v28, v2, v31
	v_mul_f32_e32 v29, v61, v33
	v_mul_f32_e32 v30, v3, v33
	v_mul_f32_e32 v31, v63, v35
	v_mul_f32_e32 v32, v4, v35
	v_mul_f32_e32 v33, v65, v37
	v_mul_f32_e32 v34, v5, v37
	v_cvt_pk_bf16_f32 v2, v0, v12
	v_cvt_pk_bf16_f32 v3, v26, v27
	v_cvt_pk_bf16_f32 v4, v13, v29
	v_cvt_pk_bf16_f32 v5, v31, v33
	v_addc_co_u32_e32 v7, vcc, 0, v7, vcc
	v_mul_f32_e32 v8, v8, v47
	v_mul_f32_e32 v9, v9, v49
	v_mul_f32_e32 v10, v10, v51
	global_store_dwordx4 v[6:7], v[2:5], off
	s_nop 1
	v_cvt_pk_bf16_f32 v2, v8, v9
	v_cvt_pk_bf16_f32 v3, v10, v11
	v_cvt_pk_bf16_f32 v4, v28, v30
	v_cvt_pk_bf16_f32 v5, v32, v34
	global_store_dwordx4 v[6:7], v[2:5], off offset:2048
	s_waitcnt lgkmcnt(0)

; __device__ __forceinline__ void tr_item(const float* __restrict__ W, int ldw, int k0, int n0, bf16* __restrict__ WT, int ldt, int drow, const float* __restrict__ mu, LAS float* scr, int lane, const float* __restrict__ gs = nullptr) {
; #pragma unroll 8
;     for (int i = 0; i < 32; ++i) { const int kk = 2 * i + (lane >> 5); scr[kk * 33 + (lane & 31)] = W[(size_t)(k0 + kk) * ldw + n0 + (lane & 31)]; }
;     asm volatile("s_waitcnt lgkmcnt(0)" ::: "memory");
.LBB0_1450:
	s_lshl_b32 s10, s8, 1
	s_lshl_b32 s11, s5, 1
	v_or_b32_e32 v0, s10, v15
	v_or_b32_e32 v50, s11, v14
	s_add_i32 s12, s10, 4
	s_add_i32 s13, s11, 4
	s_add_i32 s14, s10, 8
	s_add_i32 s15, s11, 8
	s_add_i32 s16, s10, 12
	s_add_i32 s17, s11, 12
	s_add_i32 s18, s10, 16
	s_add_i32 s19, s11, 16
	s_add_i32 s20, s10, 20
	s_add_i32 s21, s11, 20
	s_add_i32 s22, s10, 24
	s_add_i32 s23, s11, 24
	s_add_i32 s10, s10, 28
	s_add_i32 s11, s11, 28
	v_add_u32_e32 v4, s4, v50
	v_or_b32_e32 v51, s12, v15
	v_or_b32_e32 v52, s13, v14
	v_or_b32_e32 v53, s14, v15
	v_or_b32_e32 v54, s15, v14
	v_or_b32_e32 v55, s16, v15
	v_or_b32_e32 v56, s17, v14
	v_or_b32_e32 v57, s18, v15
	v_or_b32_e32 v58, s19, v14
	v_or_b32_e32 v59, s20, v15
	v_or_b32_e32 v60, s21, v14
	v_or_b32_e32 v61, s22, v15
	v_or_b32_e32 v62, s23, v14
	v_or_b32_e32 v63, s10, v15
	v_or_b32_e32 v64, s11, v14
	v_add_u32_e32 v6, s7, v0
	v_mad_u64_u32 v[4:5], s[10:11], v4, s25, v[2:3]
	v_add_u32_e32 v10, s7, v51
	v_add_u32_e32 v8, s4, v52
	v_add_u32_e32 v26, s7, v53
	s_waitcnt lgkmcnt(0)
	v_add_u32_e32 v12, s4, v54
	v_add_u32_e32 v30, s7, v55
	v_add_u32_e32 v28, s4, v56
	v_add_u32_e32 v34, s7, v57
	v_add_u32_e32 v32, s4, v58
	v_add_u32_e32 v40, s7, v59
	v_add_u32_e32 v36, s4, v60
	v_add_u32_e32 v44, s7, v61
	v_add_u32_e32 v42, s4, v62
	v_add_u32_e32 v48, s7, v63
	v_add_u32_e32 v46, s4, v64
	v_mad_u64_u32 v[6:7], s[10:11], v6, s25, v[2:3]
	v_mad_u64_u32 v[8:9], s[10:11], v8, s25, v[2:3]
	v_mad_u64_u32 v[10:11], s[10:11], v10, s25, v[2:3]
	v_mad_u64_u32 v[12:13], s[10:11], v12, s25, v[2:3]
	v_mad_u64_u32 v[26:27], s[10:11], v26, s25, v[2:3]
	v_mad_u64_u32 v[28:29], s[10:11], v28, s25, v[2:3]
	v_mad_u64_u32 v[30:31], s[10:11], v30, s25, v[2:3]
	v_mad_u64_u32 v[32:33], s[10:11], v32, s25, v[2:3]
	v_mad_u64_u32 v[34:35], s[10:11], v34, s25, v[2:3]
	v_mad_u64_u32 v[36:37], s[10:11], v36, s25, v[2:3]
	v_mad_u64_u32 v[40:41], s[10:11], v40, s25, v[2:3]
	v_mad_u64_u32 v[42:43], s[10:11], v42, s25, v[2:3]
	v_mad_u64_u32 v[44:45], s[10:11], v44, s25, v[2:3]
	v_mad_u64_u32 v[46:47], s[10:11], v46, s25, v[2:3]
	v_mad_u64_u32 v[48:49], s[10:11], v48, s25, v[2:3]
	global_load_dword v65, v[4:5], off nt
	global_load_dword v66, v[6:7], off nt
	global_load_dword v67, v[8:9], off nt
	global_load_dword v68, v[10:11], off nt
	global_load_dword v69, v[12:13], off nt
	global_load_dword v70, v[26:27], off nt
	global_load_dword v71, v[28:29], off nt
	global_load_dword v72, v[30:31], off nt
	global_load_dword v73, v[32:33], off nt
	global_load_dword v74, v[34:35], off nt
	global_load_dword v75, v[36:37], off nt
	global_load_dword v76, v[40:41], off nt
	global_load_dword v77, v[42:43], off nt
	global_load_dword v78, v[44:45], off nt
	global_load_dword v79, v[46:47], off nt
	global_load_dword v80, v[48:49], off nt
	s_add_i32 s5, s5, 16
	s_add_i32 s8, s8, 16
	s_add_i32 s9, s9, -16
	v_mad_u64_u32 v[4:5], s[10:11], v50, s26, v[18:19]
	s_cmp_lg_u32 s9, 0
	v_mad_u64_u32 v[6:7], s[10:11], v0, s26, v[18:19]
	v_mad_u64_u32 v[8:9], s[10:11], v52, s26, v[18:19]
	v_mad_u64_u32 v[10:11], s[10:11], v51, s26, v[18:19]
	v_mad_u64_u32 v[12:13], s[10:11], v54, s26, v[18:19]
	v_mad_u64_u32 v[26:27], s[10:11], v53, s26, v[18:19]
	v_mad_u64_u32 v[28:29], s[10:11], v56, s26, v[18:19]
	v_mad_u64_u32 v[30:31], s[10:11], v55, s26, v[18:19]
	v_mad_u64_u32 v[32:33], s[10:11], v58, s26, v[18:19]
	v_mad_u64_u32 v[34:35], s[10:11], v57, s26, v[18:19]
	v_mad_u64_u32 v[36:37], s[10:11], v60, s26, v[18:19]
	v_mad_u64_u32 v[40:41], s[10:11], v59, s26, v[18:19]
	v_mad_u64_u32 v[42:43], s[10:11], v62, s26, v[18:19]
	v_mad_u64_u32 v[44:45], s[10:11], v61, s26, v[18:19]
	v_mad_u64_u32 v[46:47], s[10:11], v64, s26, v[18:19]
	v_mad_u64_u32 v[48:49], s[10:11], v63, s26, v[18:19]
	s_waitcnt vmcnt(15)
	ds_write_b32 v4, v65
	s_waitcnt vmcnt(14)
	ds_write_b32 v6, v66
	s_waitcnt vmcnt(13)
	ds_write_b32 v8, v67
	s_waitcnt vmcnt(12)
	ds_write_b32 v10, v68
	s_waitcnt vmcnt(11)
	ds_write_b32 v12, v69
	s_waitcnt vmcnt(10)
	ds_write_b32 v26, v70
	s_waitcnt vmcnt(9)
	ds_write_b32 v28, v71
	s_waitcnt vmcnt(8)
	ds_write_b32 v30, v72
	s_waitcnt vmcnt(7)
	ds_write_b32 v32, v73
	s_waitcnt vmcnt(6)
	ds_write_b32 v34, v74
	s_waitcnt vmcnt(5)
	ds_write_b32 v36, v75
	s_waitcnt vmcnt(4)
	ds_write_b32 v40, v76
	s_waitcnt vmcnt(3)
	ds_write_b32 v42, v77
	s_waitcnt vmcnt(2)
	ds_write_b32 v44, v78
	s_waitcnt vmcnt(1)
	ds_write_b32 v46, v79
	s_waitcnt vmcnt(0)
	ds_write_b32 v48, v80
	s_cbranch_scc1 .LBB0_1450
; #define LAS __attribute__((address_space(3)))
; __device__ __forceinline__ v4u pack8(const float (&f)[8]) { v4u w; w.x = cvt_pk_bf16(f[0], f[1]); w.y = cvt_pk_bf16(f[2], f[3]); w.z = cvt_pk_bf16(f[4], f[5]); w.w = cvt_pk_bf16(f[6], f[7]); return w; }
; __device__ __forceinline__ void tr_item(const float* __restrict__ W, int ldw, int k0, int n0, bf16* __restrict__ WT, int ldt, int drow, const float* __restrict__ mu, LAS float* scr, int lane, const float* __restrict__ gs = nullptr) {
;     ...
;     if (mu) {
; #pragma unroll
;         for (int e = 0; e < 8; ++e) mv[e] = mu[k0 + 8 * c + e];
;     } else if (gs) {
; #pragma unroll
;         for (int e = 0; e < 8; ++e) mv[e] = gs[k0 + 8 * c + e];
;     }
; #pragma unroll
;     for (int j = 0; j < 4; ++j) {
;         const int n = (lane >> 3) + 8 * j; const LAS float* s = scr + (8 * c) * 33 + n;
;         float f[8];
; #pragma unroll
;         for (int e = 0; e < 8; ++e) f[e] = s[e * 33];
;         bf16* dp = WT + (size_t)(drow + n) * ldt + k0 + 8 * c;
;         if (mu) {
;             float f1[8], f2[8];
; #pragma unroll
;             for (int e = 0; e < 8; ++e) { f1[e] = f[e] * (1.f - mv[e]); f2[e] = f[e] * mv[e]; }
;             *(v4u*)dp = pack8(f1); *(v4u*)(dp + 1024) = pack8(f2);
;         } else { if (gs) {
; #pragma unroll
;             for (int e = 0; e < 8; ++e) f[e] *= mv[e]; }
;             *(v4u*)dp = pack8(f); }
;     }
; __device__ __forceinline__ void ph_p0(const Params& p, LAS unsigned char* lds, int tid, int lane, int wave) {
;     ...
;         if (r < C_G1) { const int j = r / 80, q = r % 80, kb = q / 5, nb = q % 5;
;             tr_item(p.in[I_G1] + (size_t)j * D * LG, LG, 64 * kb, 32 * nb, (bf16*)(ws + WS_WRW + j * SZ_WRW), KRW, 3200 + 32 * nb, p.in[I_MU] + (size_t)(j * 6 + 5) * D, scr, lane); continue; }
	s_and_b64 s[8:9], s[0:1], exec
	s_cselect_b32 s5, 0xe00000, 0
	s_add_u32 s5, s36, s5
	s_addc_u32 s7, s37, 0
	s_and_b64 s[0:1], s[0:1], exec
	s_mov_b32 s0, 0xb000
	s_cselect_b32 s1, s0, 0x5000
	s_add_i32 s0, s94, 0xc80
	s_add_u32 s8, s50, s1
	s_addc_u32 s9, s51, 0
	v_or_b32_e32 v0, s4, v20
	s_waitcnt lgkmcnt(0)
	v_lshl_add_u64 v[6:7], v[0:1], 2, s[8:9]
	global_load_dwordx4 v[2:5], v[6:7], off
	s_nop 0
	global_load_dwordx4 v[6:9], v[6:7], off offset:16
	ds_read2_b32 v[26:27], v19 offset0:33 offset1:41
	ds_read2_b32 v[28:29], v19 offset0:66 offset1:74
	ds_read2_b32 v[30:31], v19 offset0:99 offset1:107
	ds_read2_b32 v[32:33], v19 offset0:132 offset1:140
	ds_read2_b32 v[34:35], v19 offset0:165 offset1:173
	ds_read2_b32 v[36:37], v19 offset0:198 offset1:206
	ds_read2_b32 v[40:41], v19 offset0:231 offset1:239
	ds_read2_b32 v[42:43], v19 offset1:8
	s_lshl_b32 s1, s4, 1
	s_add_u32 s4, s5, s1
	v_or_b32_e32 v10, s0, v17
	v_lshlrev_b32_e32 v0, 1, v20
	s_addc_u32 s5, s7, 0
	v_or_b32_e32 v11, s0, v21
	v_lshl_add_u64 v[44:45], s[4:5], 0, v[0:1]
	v_lshlrev_b32_e32 v0, 12, v10
	v_lshl_add_u64 v[46:47], v[44:45], 0, v[0:1]
	v_lshlrev_b32_e32 v0, 12, v11
	v_lshl_add_u64 v[48:49], v[44:45], 0, v[0:1]
	s_waitcnt vmcnt(1)
	v_sub_f32_e32 v50, 1.0, v2
	s_waitcnt lgkmcnt(0)
	v_mul_f32_e32 v0, v2, v42
	v_sub_f32_e32 v51, 1.0, v3
	v_mul_f32_e32 v10, v3, v26
	v_sub_f32_e32 v52, 1.0, v4
	v_mul_f32_e32 v11, v4, v28
	v_mul_f32_e32 v12, v5, v30
	s_waitcnt vmcnt(0)
	v_sub_f32_e32 v54, 1.0, v6
	v_mul_f32_e32 v13, v6, v32
	v_mul_f32_e32 v56, v7, v34
	v_sub_f32_e32 v53, 1.0, v5
	v_sub_f32_e32 v55, 1.0, v7
	v_sub_f32_e32 v57, 1.0, v8
	v_mul_f32_e32 v58, v8, v36
	v_sub_f32_e32 v59, 1.0, v9
	v_mul_f32_e32 v60, v9, v40
	v_mul_f32_e32 v61, v2, v43
	v_mul_f32_e32 v62, v3, v27
	v_mul_f32_e32 v63, v4, v29
	v_mul_f32_e32 v64, v5, v31
	v_mul_f32_e32 v65, v6, v33
	v_mul_f32_e32 v66, v7, v35
	v_mul_f32_e32 v67, v8, v37
	v_mul_f32_e32 v68, v9, v41
	v_mul_f32_e32 v69, v51, v26
	v_mul_f32_e32 v70, v52, v28
	v_mul_f32_e32 v32, v54, v32
	v_cvt_pk_bf16_f32 v10, v0, v10
	v_cvt_pk_bf16_f32 v11, v11, v12
	v_cvt_pk_bf16_f32 v12, v13, v56
	v_cvt_pk_bf16_f32 v13, v58, v60
	v_mul_f32_e32 v0, v50, v43
	v_mul_f32_e32 v43, v51, v27
	v_mul_f32_e32 v56, v52, v29
	v_cvt_pk_bf16_f32 v26, v61, v62
	v_cvt_pk_bf16_f32 v27, v63, v64
	v_cvt_pk_bf16_f32 v28, v65, v66
	v_cvt_pk_bf16_f32 v29, v67, v68
	v_mul_f32_e32 v42, v50, v42
	v_mul_f32_e32 v71, v53, v30
	v_mul_f32_e32 v34, v55, v34
	v_mul_f32_e32 v36, v57, v36
	v_mul_f32_e32 v40, v59, v40
	v_mul_f32_e32 v58, v53, v31
	v_mul_f32_e32 v60, v54, v33
	v_mul_f32_e32 v35, v55, v35
	v_mul_f32_e32 v37, v57, v37
	v_mul_f32_e32 v41, v59, v41
	v_cvt_pk_bf16_f32 v30, v42, v69
	v_cvt_pk_bf16_f32 v31, v70, v71
	v_cvt_pk_bf16_f32 v32, v32, v34
	v_cvt_pk_bf16_f32 v33, v36, v40
	global_store_dwordx4 v[46:47], v[10:13], off offset:2048
	s_nop 1
	v_cvt_pk_bf16_f32 v10, v0, v43
	v_cvt_pk_bf16_f32 v11, v56, v58
	v_cvt_pk_bf16_f32 v12, v60, v35
	v_cvt_pk_bf16_f32 v13, v37, v41
	global_store_dwordx4 v[48:49], v[26:29], off offset:2048
	global_store_dwordx4 v[46:47], v[30:33], off
	global_store_dwordx4 v[48:49], v[10:13], off
	ds_read2_b32 v[26:27], v19 offset0:16 offset1:24
	ds_read2_b32 v[28:29], v19 offset0:49 offset1:57
	ds_read2_b32 v[30:31], v19 offset0:82 offset1:90
	ds_read2_b32 v[32:33], v19 offset0:115 offset1:123
	ds_read2_b32 v[34:35], v19 offset0:148 offset1:156
	ds_read2_b32 v[36:37], v19 offset0:181 offset1:189
	ds_read2_b32 v[40:41], v19 offset0:214 offset1:222
	ds_read2_b32 v[42:43], v19 offset0:247 offset1:255
	v_or_b32_e32 v0, s0, v38
	v_lshlrev_b32_e32 v0, 12, v0
	v_lshl_add_u64 v[46:47], v[44:45], 0, v[0:1]
	s_waitcnt lgkmcnt(7)
	v_mul_f32_e32 v0, v50, v26
	s_waitcnt lgkmcnt(6)
	v_mul_f32_e32 v10, v51, v28
	s_waitcnt lgkmcnt(5)
	v_mul_f32_e32 v11, v52, v30
	s_waitcnt lgkmcnt(4)
	v_mul_f32_e32 v12, v53, v32
	s_waitcnt lgkmcnt(3)
	v_mul_f32_e32 v13, v54, v34
	s_waitcnt lgkmcnt(2)
	v_mul_f32_e32 v48, v55, v36
	s_waitcnt lgkmcnt(1)
	v_mul_f32_e32 v49, v57, v40
	s_waitcnt lgkmcnt(0)
	v_mul_f32_e32 v56, v59, v42
	v_cvt_pk_bf16_f32 v10, v0, v10
	v_cvt_pk_bf16_f32 v11, v11, v12
	v_cvt_pk_bf16_f32 v12, v13, v48
	v_cvt_pk_bf16_f32 v13, v49, v56
	v_or_b32_e32 v0, s0, v39
	v_mul_f32_e32 v26, v2, v26
	v_mul_f32_e32 v28, v3, v28
	v_mul_f32_e32 v30, v4, v30
	v_mul_f32_e32 v32, v5, v32
	v_mul_f32_e32 v34, v6, v34
	v_mul_f32_e32 v36, v7, v36
	v_mul_f32_e32 v40, v8, v40
	v_mul_f32_e32 v42, v9, v42
	global_store_dwordx4 v[46:47], v[10:13], off
	v_lshlrev_b32_e32 v0, 12, v0
	v_mul_f32_e32 v6, v6, v35
	v_cvt_pk_bf16_f32 v10, v26, v28
	v_cvt_pk_bf16_f32 v11, v30, v32
	v_cvt_pk_bf16_f32 v12, v34, v36
	v_cvt_pk_bf16_f32 v13, v40, v42
	global_store_dwordx4 v[46:47], v[10:13], off offset:2048
	v_mul_f32_e32 v26, v4, v31
	v_mul_f32_e32 v4, v53, v33
	v_lshl_add_u64 v[10:11], v[44:45], 0, v[0:1]
	v_mul_f32_e32 v0, v50, v27
	v_mul_f32_e32 v12, v2, v27
	v_mul_f32_e32 v2, v51, v29
	v_mul_f32_e32 v13, v3, v29
	v_mul_f32_e32 v3, v52, v31
	v_mul_f32_e32 v27, v5, v33
	v_mul_f32_e32 v5, v54, v35
	v_mul_f32_e32 v28, v55, v37
	v_mul_f32_e32 v29, v57, v41
	v_mul_f32_e32 v30, v59, v43
	v_cvt_pk_bf16_f32 v2, v0, v2
	v_cvt_pk_bf16_f32 v3, v3, v4
	v_cvt_pk_bf16_f32 v4, v5, v28
	v_cvt_pk_bf16_f32 v5, v29, v30
	v_mul_f32_e32 v7, v7, v37
	v_mul_f32_e32 v8, v8, v41
	v_mul_f32_e32 v9, v9, v43
	global_store_dwordx4 v[10:11], v[2:5], off
	s_nop 1
	v_cvt_pk_bf16_f32 v2, v12, v13
	v_cvt_pk_bf16_f32 v3, v26, v27
	v_cvt_pk_bf16_f32 v4, v6, v7
	v_cvt_pk_bf16_f32 v5, v8, v9
	global_store_dwordx4 v[10:11], v[2:5], off offset:2048
	s_waitcnt lgkmcnt(0)

; __device__ __forceinline__ void tr_item(const float* __restrict__ W, int ldw, int k0, int n0, bf16* __restrict__ WT, int ldt, int drow, const float* __restrict__ mu, LAS float* scr, int lane, const float* __restrict__ gs = nullptr) {
; #pragma unroll 8
;     for (int i = 0; i < 32; ++i) { const int kk = 2 * i + (lane >> 5); scr[kk * 33 + (lane & 31)] = W[(size_t)(k0 + kk) * ldw + n0 + (lane & 31)]; }
;     asm volatile("s_waitcnt lgkmcnt(0)" ::: "memory");
.LBB0_1455:
	s_lshl_b32 s9, s7, 1
	s_lshl_b32 s10, s8, 1
	v_or_b32_e32 v41, s10, v14
	s_add_i32 s11, s9, 4
	s_add_i32 s12, s10, 4
	s_add_i32 s14, s10, 8
	v_add_u32_e32 v0, s0, v41
	v_or_b32_e32 v42, s11, v15
	v_or_b32_e32 v43, s12, v14
	v_mov_b32_e32 v7, v1
	v_or_b32_e32 v40, s9, v15
	s_add_i32 s16, s10, 12
	v_or_b32_e32 v45, s14, v14
	s_waitcnt lgkmcnt(3)
	v_lshlrev_b64 v[32:33], 8, v[0:1]
	v_add_u32_e32 v6, s5, v42
	v_add_u32_e32 v0, s0, v43
	v_mov_b32_e32 v5, v1
	s_add_i32 s13, s9, 8
	s_add_i32 s15, s9, 12
	s_add_i32 s18, s10, 16
	v_add_u32_e32 v4, s5, v40
	v_or_b32_e32 v47, s16, v14
	v_lshlrev_b64 v[6:7], 8, v[6:7]
	v_lshlrev_b64 v[34:35], 8, v[0:1]
	v_add_u32_e32 v0, s0, v45
	s_add_i32 s20, s10, 20
	v_or_b32_e32 v44, s13, v15
	v_or_b32_e32 v46, s15, v15
	v_or_b32_e32 v49, s18, v14
	v_lshlrev_b64 v[4:5], 8, v[4:5]
	v_lshl_add_u64 v[32:33], v[2:3], 0, v[32:33]
	v_lshl_add_u64 v[6:7], v[2:3], 0, v[6:7]
	v_lshlrev_b64 v[36:37], 8, v[0:1]
	v_add_u32_e32 v0, s0, v47
	v_mov_b32_e32 v9, v1
	v_mov_b32_e32 v11, v1
	s_add_i32 s17, s9, 16
	s_add_i32 s19, s9, 20
	s_add_i32 s22, s10, 24
	v_or_b32_e32 v51, s20, v14
	v_add_u32_e32 v8, s5, v44
	v_add_u32_e32 v10, s5, v46
	v_lshl_add_u64 v[4:5], v[2:3], 0, v[4:5]
	v_lshl_add_u64 v[34:35], v[2:3], 0, v[34:35]
	global_load_dword v56, v[32:33], off nt
	global_load_dword v57, v[4:5], off nt
	global_load_dword v58, v[34:35], off nt
	global_load_dword v59, v[6:7], off nt
	v_lshlrev_b64 v[6:7], 8, v[0:1]
	v_add_u32_e32 v0, s0, v49
	s_add_i32 s21, s9, 24
	s_add_i32 s9, s9, 28
	s_add_i32 s10, s10, 28
	v_or_b32_e32 v48, s17, v15
	v_or_b32_e32 v50, s19, v15
	v_or_b32_e32 v53, s22, v14
	v_lshlrev_b64 v[8:9], 8, v[8:9]
	v_lshlrev_b64 v[10:11], 8, v[10:11]
	v_lshl_add_u64 v[4:5], v[2:3], 0, v[36:37]
	v_lshl_add_u64 v[6:7], v[2:3], 0, v[6:7]
	v_lshlrev_b64 v[32:33], 8, v[0:1]
	v_add_u32_e32 v0, s0, v51
	s_waitcnt lgkmcnt(0)
	v_mov_b32_e32 v13, v1
	v_mov_b32_e32 v27, v1
	v_or_b32_e32 v52, s21, v15
	v_or_b32_e32 v54, s9, v15
	v_or_b32_e32 v55, s10, v14
	v_add_u32_e32 v12, s5, v48
	v_add_u32_e32 v26, s5, v50
	v_lshl_add_u64 v[8:9], v[2:3], 0, v[8:9]
	v_lshl_add_u64 v[10:11], v[2:3], 0, v[10:11]
	global_load_dword v60, v[4:5], off nt
	global_load_dword v61, v[8:9], off nt
	global_load_dword v62, v[6:7], off nt
	global_load_dword v63, v[10:11], off nt
	v_lshlrev_b64 v[6:7], 8, v[0:1]
	v_add_u32_e32 v0, s0, v53
	v_mov_b32_e32 v29, v1
	v_mov_b32_e32 v31, v1
	v_add_u32_e32 v28, s5, v52
	v_add_u32_e32 v30, s5, v54
	v_lshlrev_b64 v[12:13], 8, v[12:13]
	v_lshlrev_b64 v[26:27], 8, v[26:27]
	v_lshl_add_u64 v[4:5], v[2:3], 0, v[32:33]
	v_lshl_add_u64 v[6:7], v[2:3], 0, v[6:7]
	v_lshlrev_b64 v[8:9], 8, v[0:1]
	v_add_u32_e32 v0, s0, v55
	v_lshlrev_b64 v[28:29], 8, v[28:29]
	v_lshlrev_b64 v[30:31], 8, v[30:31]
	v_lshl_add_u64 v[12:13], v[2:3], 0, v[12:13]
	v_lshl_add_u64 v[26:27], v[2:3], 0, v[26:27]
	global_load_dword v64, v[4:5], off nt
	global_load_dword v65, v[12:13], off nt
	global_load_dword v66, v[6:7], off nt
	global_load_dword v67, v[26:27], off nt
	v_lshl_add_u64 v[4:5], v[2:3], 0, v[8:9]
	v_lshlrev_b64 v[6:7], 8, v[0:1]
	v_lshl_add_u64 v[28:29], v[2:3], 0, v[28:29]
	v_lshl_add_u64 v[30:31], v[2:3], 0, v[30:31]
	v_lshl_add_u64 v[6:7], v[2:3], 0, v[6:7]
	global_load_dword v0, v[4:5], off nt
	global_load_dword v68, v[28:29], off nt
	global_load_dword v69, v[6:7], off nt
	global_load_dword v70, v[30:31], off nt
	s_add_i32 s8, s8, 16
	s_add_i32 s7, s7, 16
	s_add_i32 s4, s4, -16
	v_mad_u64_u32 v[4:5], s[10:11], v41, s26, v[18:19]
	s_cmp_lg_u32 s4, 0
	v_mad_u64_u32 v[6:7], s[10:11], v40, s26, v[18:19]
	v_mad_u64_u32 v[8:9], s[10:11], v43, s26, v[18:19]
	v_mad_u64_u32 v[10:11], s[10:11], v42, s26, v[18:19]
	v_mad_u64_u32 v[12:13], s[10:11], v45, s26, v[18:19]
	v_mad_u64_u32 v[26:27], s[10:11], v44, s26, v[18:19]
	v_mad_u64_u32 v[28:29], s[10:11], v47, s26, v[18:19]
	v_mad_u64_u32 v[30:31], s[10:11], v46, s26, v[18:19]
	v_mad_u64_u32 v[32:33], s[10:11], v49, s26, v[18:19]
	v_mad_u64_u32 v[34:35], s[10:11], v48, s26, v[18:19]
	v_mad_u64_u32 v[36:37], s[10:11], v51, s26, v[18:19]
	v_mad_u64_u32 v[40:41], s[10:11], v50, s26, v[18:19]
	v_mad_u64_u32 v[42:43], s[10:11], v53, s26, v[18:19]
	v_mad_u64_u32 v[44:45], s[10:11], v52, s26, v[18:19]
	v_mad_u64_u32 v[46:47], s[10:11], v55, s26, v[18:19]
	v_mad_u64_u32 v[48:49], s[10:11], v54, s26, v[18:19]
	s_waitcnt vmcnt(15)
	ds_write_b32 v4, v56
	s_waitcnt vmcnt(14)
	ds_write_b32 v6, v57
	s_waitcnt vmcnt(13)
	ds_write_b32 v8, v58
	s_waitcnt vmcnt(12)
	ds_write_b32 v10, v59
	s_waitcnt vmcnt(11)
	ds_write_b32 v12, v60
	s_waitcnt vmcnt(10)
	ds_write_b32 v26, v61
	s_waitcnt vmcnt(9)
	ds_write_b32 v28, v62
	s_waitcnt vmcnt(8)
	ds_write_b32 v30, v63
	s_waitcnt vmcnt(7)
	ds_write_b32 v32, v64
	s_waitcnt vmcnt(6)
	ds_write_b32 v34, v65
	s_waitcnt vmcnt(5)
	ds_write_b32 v36, v66
	s_waitcnt vmcnt(4)
	ds_write_b32 v40, v67
	s_waitcnt vmcnt(3)
	ds_write_b32 v42, v0
	s_waitcnt vmcnt(2)
	ds_write_b32 v44, v68
	s_waitcnt vmcnt(1)
	ds_write_b32 v46, v69
	s_waitcnt vmcnt(0)
	ds_write_b32 v48, v70
	s_cbranch_scc1 .LBB0_1455
; #define LAS __attribute__((address_space(3)))
; __device__ __forceinline__ v4u pack8(const float (&f)[8]) { v4u w; w.x = cvt_pk_bf16(f[0], f[1]); w.y = cvt_pk_bf16(f[2], f[3]); w.z = cvt_pk_bf16(f[4], f[5]); w.w = cvt_pk_bf16(f[6], f[7]); return w; }
; __device__ __forceinline__ void tr_item(const float* __restrict__ W, int ldw, int k0, int n0, bf16* __restrict__ WT, int ldt, int drow, const float* __restrict__ mu, LAS float* scr, int lane, const float* __restrict__ gs = nullptr) {
;     ...
;     if (mu) {
; #pragma unroll
;         for (int e = 0; e < 8; ++e) mv[e] = mu[k0 + 8 * c + e];
;     } else if (gs) {
; #pragma unroll
;         for (int e = 0; e < 8; ++e) mv[e] = gs[k0 + 8 * c + e];
;     }
; #pragma unroll
;     for (int j = 0; j < 4; ++j) {
;         const int n = (lane >> 3) + 8 * j; const LAS float* s = scr + (8 * c) * 33 + n;
;         float f[8];
; #pragma unroll
;         for (int e = 0; e < 8; ++e) f[e] = s[e * 33];
;         bf16* dp = WT + (size_t)(drow + n) * ldt + k0 + 8 * c;
;         if (mu) {
;             float f1[8], f2[8];
; #pragma unroll
;             for (int e = 0; e < 8; ++e) { f1[e] = f[e] * (1.f - mv[e]); f2[e] = f[e] * mv[e]; }
;             *(v4u*)dp = pack8(f1); *(v4u*)(dp + 1024) = pack8(f2);
;         } else { if (gs) {
; #pragma unroll
;             for (int e = 0; e < 8; ++e) f[e] *= mv[e]; }
;             *(v4u*)dp = pack8(f); }
;     }
; __device__ __forceinline__ void ph_p0(const Params& p, LAS unsigned char* lds, int tid, int lane, int wave) {
;     ...
;         if (r < C_A1) { const int j = r / 32, q = r % 32, kb = q / 2, nb = q % 2;
;             tr_item(p.in[I_A1] + (size_t)j * D * LA, LA, 64 * kb, 32 * nb, (bf16*)(ws + WS_WRW + j * SZ_WRW), KRW, 3136 + 32 * nb, p.in[I_MU] + (size_t)(j * 6 + 4) * D, scr, lane); continue; }
	s_mul_i32 s7, s94, 6
	s_mul_hi_u32 s4, s94, 0xe00000
	s_mul_i32 s5, s94, 0xe00000
	s_add_i32 s94, s7, 4
	s_add_u32 s7, s36, s5
	s_addc_u32 s8, s37, s4
	s_lshl_b64 s[4:5], s[94:95], 12
	s_or_b32 s1, s1, 0xc40
	s_add_u32 s4, s50, s4
	v_or_b32_e32 v0, s0, v20
	s_addc_u32 s5, s51, s5
	s_waitcnt lgkmcnt(0)
	v_lshlrev_b32_e32 v0, 2, v0
	global_load_dwordx4 v[2:5], v0, s[4:5]
	global_load_dwordx4 v[6:9], v0, s[4:5] offset:16
	ds_read2_b32 v[26:27], v19 offset0:33 offset1:41
	ds_read2_b32 v[28:29], v19 offset0:66 offset1:74
	ds_read2_b32 v[30:31], v19 offset0:99 offset1:107
	ds_read2_b32 v[32:33], v19 offset0:132 offset1:140
	ds_read2_b32 v[34:35], v19 offset0:165 offset1:173
	ds_read2_b32 v[36:37], v19 offset0:198 offset1:206
	ds_read2_b32 v[40:41], v19 offset0:231 offset1:239
	ds_read2_b32 v[42:43], v19 offset1:8
	s_lshl_b32 s0, s0, 1
	s_add_u32 s4, s7, s0
	v_lshlrev_b32_e32 v0, 1, v20
	v_or_b32_e32 v10, s1, v17
	s_addc_u32 s5, s8, 0
	v_or_b32_e32 v11, s1, v21
	v_lshl_add_u64 v[44:45], s[4:5], 0, v[0:1]
	v_lshlrev_b32_e32 v0, 12, v10
	v_lshl_add_u64 v[46:47], v[44:45], 0, v[0:1]
	v_lshlrev_b32_e32 v0, 12, v11
	v_lshl_add_u64 v[48:49], v[44:45], 0, v[0:1]
	s_waitcnt vmcnt(1)
	v_sub_f32_e32 v53, 1.0, v5
	v_sub_f32_e32 v50, 1.0, v2
	s_waitcnt lgkmcnt(0)
	v_mul_f32_e32 v0, v2, v42
	v_sub_f32_e32 v51, 1.0, v3
	v_mul_f32_e32 v10, v3, v26
	v_sub_f32_e32 v52, 1.0, v4
	v_mul_f32_e32 v11, v4, v28
	v_mul_f32_e32 v12, v5, v30
	s_waitcnt vmcnt(0)
	v_sub_f32_e32 v54, 1.0, v6
	v_mul_f32_e32 v13, v6, v32
	v_sub_f32_e32 v55, 1.0, v7
	v_mul_f32_e32 v56, v7, v34
	v_sub_f32_e32 v57, 1.0, v8
	v_sub_f32_e32 v59, 1.0, v9
	v_mul_f32_e32 v30, v53, v30
	v_mul_f32_e32 v58, v8, v36
	v_mul_f32_e32 v60, v9, v40
	v_mul_f32_e32 v61, v2, v43
	v_mul_f32_e32 v62, v3, v27
	v_mul_f32_e32 v63, v4, v29
	v_mul_f32_e32 v64, v5, v31
	v_mul_f32_e32 v42, v50, v42
	v_mul_f32_e32 v69, v51, v26
	v_mul_f32_e32 v70, v52, v28
	v_mul_f32_e32 v32, v54, v32
	v_mul_f32_e32 v34, v55, v34
	v_mul_f32_e32 v36, v57, v36
	v_mul_f32_e32 v40, v59, v40
	v_cvt_pk_bf16_f32 v10, v0, v10
	v_cvt_pk_bf16_f32 v11, v11, v12
	v_cvt_pk_bf16_f32 v12, v13, v56
	v_cvt_pk_bf16_f32 v13, v58, v60
	v_mul_f32_e32 v0, v50, v43
	v_mul_f32_e32 v27, v51, v27
	v_mul_f32_e32 v43, v52, v29
	v_mul_f32_e32 v56, v53, v31
	v_cvt_pk_bf16_f32 v28, v42, v69
	v_cvt_pk_bf16_f32 v29, v70, v30
	v_cvt_pk_bf16_f32 v30, v32, v34
	v_cvt_pk_bf16_f32 v31, v36, v40
	v_mul_f32_e32 v65, v6, v33
	v_mul_f32_e32 v66, v7, v35
	v_mul_f32_e32 v67, v8, v37
	v_mul_f32_e32 v68, v9, v41
	v_mul_f32_e32 v33, v54, v33
	v_mul_f32_e32 v35, v55, v35
	v_mul_f32_e32 v37, v57, v37
	v_mul_f32_e32 v41, v59, v41
	v_cvt_pk_bf16_f32 v26, v61, v62
	global_store_dwordx4 v[46:47], v[10:13], off offset:2048
	s_nop 1
	v_cvt_pk_bf16_f32 v10, v0, v27
	v_cvt_pk_bf16_f32 v11, v43, v56
	v_cvt_pk_bf16_f32 v12, v33, v35
	v_cvt_pk_bf16_f32 v13, v37, v41
	global_store_dwordx4 v[46:47], v[28:31], off
	global_store_dwordx4 v[48:49], v[10:13], off
	v_cvt_pk_bf16_f32 v27, v63, v64
	v_or_b32_e32 v0, s1, v38
	v_cvt_pk_bf16_f32 v28, v65, v66
	v_cvt_pk_bf16_f32 v29, v67, v68
	global_store_dwordx4 v[48:49], v[26:29], off offset:2048
	ds_read2_b32 v[26:27], v19 offset0:16 offset1:24
	ds_read2_b32 v[28:29], v19 offset0:49 offset1:57
	ds_read2_b32 v[30:31], v19 offset0:82 offset1:90
	ds_read2_b32 v[32:33], v19 offset0:115 offset1:123
	ds_read2_b32 v[34:35], v19 offset0:148 offset1:156
	ds_read2_b32 v[36:37], v19 offset0:181 offset1:189
	ds_read2_b32 v[40:41], v19 offset0:214 offset1:222
	ds_read2_b32 v[42:43], v19 offset0:247 offset1:255
	v_lshlrev_b32_e32 v0, 12, v0
	v_lshl_add_u64 v[46:47], v[44:45], 0, v[0:1]
	s_waitcnt lgkmcnt(7)
	v_mul_f32_e32 v0, v50, v26
	s_waitcnt lgkmcnt(6)
	v_mul_f32_e32 v10, v51, v28
	s_waitcnt lgkmcnt(5)
	v_mul_f32_e32 v11, v52, v30
	s_waitcnt lgkmcnt(4)
	v_mul_f32_e32 v12, v53, v32
	s_waitcnt lgkmcnt(3)
	v_mul_f32_e32 v13, v54, v34
	s_waitcnt lgkmcnt(2)
	v_mul_f32_e32 v48, v55, v36
	s_waitcnt lgkmcnt(1)
	v_mul_f32_e32 v49, v57, v40
	s_waitcnt lgkmcnt(0)
	v_mul_f32_e32 v56, v59, v42
	v_cvt_pk_bf16_f32 v10, v0, v10
	v_cvt_pk_bf16_f32 v11, v11, v12
	v_cvt_pk_bf16_f32 v12, v13, v48
	v_cvt_pk_bf16_f32 v13, v49, v56
	v_or_b32_e32 v0, s1, v39
	v_mul_f32_e32 v26, v2, v26
	v_mul_f32_e32 v28, v3, v28
	v_mul_f32_e32 v30, v4, v30
	v_mul_f32_e32 v32, v5, v32
	v_mul_f32_e32 v34, v6, v34
	v_mul_f32_e32 v36, v7, v36
	v_mul_f32_e32 v40, v8, v40
	v_mul_f32_e32 v42, v9, v42
	global_store_dwordx4 v[46:47], v[10:13], off
	v_lshlrev_b32_e32 v0, 12, v0
	v_mul_f32_e32 v6, v6, v35
	v_cvt_pk_bf16_f32 v10, v26, v28
	v_cvt_pk_bf16_f32 v11, v30, v32
	v_cvt_pk_bf16_f32 v12, v34, v36
	v_cvt_pk_bf16_f32 v13, v40, v42
	global_store_dwordx4 v[46:47], v[10:13], off offset:2048
	v_mul_f32_e32 v26, v4, v31
	v_mul_f32_e32 v4, v53, v33
	v_lshl_add_u64 v[10:11], v[44:45], 0, v[0:1]
	v_mul_f32_e32 v0, v50, v27
	v_mul_f32_e32 v12, v2, v27
	v_mul_f32_e32 v2, v51, v29
	v_mul_f32_e32 v13, v3, v29
	v_mul_f32_e32 v3, v52, v31
	v_mul_f32_e32 v27, v5, v33
	v_mul_f32_e32 v5, v54, v35
	v_mul_f32_e32 v28, v55, v37
	v_mul_f32_e32 v29, v57, v41
	v_mul_f32_e32 v30, v59, v43
	v_cvt_pk_bf16_f32 v2, v0, v2
	v_cvt_pk_bf16_f32 v3, v3, v4
	v_cvt_pk_bf16_f32 v4, v5, v28
	v_cvt_pk_bf16_f32 v5, v29, v30
	v_mul_f32_e32 v7, v7, v37
	v_mul_f32_e32 v8, v8, v41
	v_mul_f32_e32 v9, v9, v43
	global_store_dwordx4 v[10:11], v[2:5], off
	s_nop 1
	v_cvt_pk_bf16_f32 v2, v12, v13
	v_cvt_pk_bf16_f32 v3, v26, v27
	v_cvt_pk_bf16_f32 v4, v6, v7
	v_cvt_pk_bf16_f32 v5, v8, v9
	global_store_dwordx4 v[10:11], v[2:5], off offset:2048
	s_waitcnt lgkmcnt(0)

; __device__ __forceinline__ void tr_item(const float* __restrict__ W, int ldw, int k0, int n0, bf16* __restrict__ WT, int ldt, int drow, const float* __restrict__ mu, LAS float* scr, int lane, const float* __restrict__ gs = nullptr) {
; #pragma unroll 8
;     for (int i = 0; i < 32; ++i) { const int kk = 2 * i + (lane >> 5); scr[kk * 33 + (lane & 31)] = W[(size_t)(k0 + kk) * ldw + n0 + (lane & 31)]; }
;     asm volatile("s_waitcnt lgkmcnt(0)" ::: "memory");
.LBB0_1460:
	s_lshl_b32 s9, s7, 1
	s_lshl_b32 s10, s8, 1
	v_or_b32_e32 v41, s10, v14
	s_add_i32 s11, s9, 4
	s_add_i32 s12, s10, 4
	s_add_i32 s14, s10, 8
	v_add_u32_e32 v0, s0, v41
	v_or_b32_e32 v42, s11, v15
	v_or_b32_e32 v43, s12, v14
	v_mov_b32_e32 v7, v1
	v_or_b32_e32 v40, s9, v15
	s_add_i32 s16, s10, 12
	v_or_b32_e32 v45, s14, v14
	s_waitcnt lgkmcnt(3)
	v_lshlrev_b64 v[32:33], 8, v[0:1]
	v_add_u32_e32 v6, s5, v42
	v_add_u32_e32 v0, s0, v43
	v_mov_b32_e32 v5, v1
	s_add_i32 s13, s9, 8
	s_add_i32 s15, s9, 12
	s_add_i32 s18, s10, 16
	v_add_u32_e32 v4, s5, v40
	v_or_b32_e32 v47, s16, v14
	v_lshlrev_b64 v[6:7], 8, v[6:7]
	v_lshlrev_b64 v[34:35], 8, v[0:1]
	v_add_u32_e32 v0, s0, v45
	s_add_i32 s20, s10, 20
	v_or_b32_e32 v44, s13, v15
	v_or_b32_e32 v46, s15, v15
	v_or_b32_e32 v49, s18, v14
	v_lshlrev_b64 v[4:5], 8, v[4:5]
	v_lshl_add_u64 v[32:33], v[2:3], 0, v[32:33]
	v_lshl_add_u64 v[6:7], v[2:3], 0, v[6:7]
	v_lshlrev_b64 v[36:37], 8, v[0:1]
	v_add_u32_e32 v0, s0, v47
	v_mov_b32_e32 v9, v1
	v_mov_b32_e32 v11, v1
	s_add_i32 s17, s9, 16
	s_add_i32 s19, s9, 20
	s_add_i32 s22, s10, 24
	v_or_b32_e32 v51, s20, v14
	v_add_u32_e32 v8, s5, v44
	v_add_u32_e32 v10, s5, v46
	v_lshl_add_u64 v[4:5], v[2:3], 0, v[4:5]
	v_lshl_add_u64 v[34:35], v[2:3], 0, v[34:35]
	global_load_dword v56, v[32:33], off nt
	global_load_dword v57, v[4:5], off nt
	global_load_dword v58, v[34:35], off nt
	global_load_dword v59, v[6:7], off nt
	v_lshlrev_b64 v[6:7], 8, v[0:1]
	v_add_u32_e32 v0, s0, v49
	s_add_i32 s21, s9, 24
	s_add_i32 s9, s9, 28
	s_add_i32 s10, s10, 28
	v_or_b32_e32 v48, s17, v15
	v_or_b32_e32 v50, s19, v15
	v_or_b32_e32 v53, s22, v14
	v_lshlrev_b64 v[8:9], 8, v[8:9]
	v_lshlrev_b64 v[10:11], 8, v[10:11]
	v_lshl_add_u64 v[4:5], v[2:3], 0, v[36:37]
	v_lshl_add_u64 v[6:7], v[2:3], 0, v[6:7]
	v_lshlrev_b64 v[32:33], 8, v[0:1]
	v_add_u32_e32 v0, s0, v51
	s_waitcnt lgkmcnt(0)
	v_mov_b32_e32 v13, v1
	v_mov_b32_e32 v27, v1
	v_or_b32_e32 v52, s21, v15
	v_or_b32_e32 v54, s9, v15
	v_or_b32_e32 v55, s10, v14
	v_add_u32_e32 v12, s5, v48
	v_add_u32_e32 v26, s5, v50
	v_lshl_add_u64 v[8:9], v[2:3], 0, v[8:9]
	v_lshl_add_u64 v[10:11], v[2:3], 0, v[10:11]
	global_load_dword v60, v[4:5], off nt
	global_load_dword v61, v[8:9], off nt
	global_load_dword v62, v[6:7], off nt
	global_load_dword v63, v[10:11], off nt
	v_lshlrev_b64 v[6:7], 8, v[0:1]
	v_add_u32_e32 v0, s0, v53
	v_mov_b32_e32 v29, v1
	v_mov_b32_e32 v31, v1
	v_add_u32_e32 v28, s5, v52
	v_add_u32_e32 v30, s5, v54
	v_lshlrev_b64 v[12:13], 8, v[12:13]
	v_lshlrev_b64 v[26:27], 8, v[26:27]
	v_lshl_add_u64 v[4:5], v[2:3], 0, v[32:33]
	v_lshl_add_u64 v[6:7], v[2:3], 0, v[6:7]
	v_lshlrev_b64 v[8:9], 8, v[0:1]
	v_add_u32_e32 v0, s0, v55
	v_lshlrev_b64 v[28:29], 8, v[28:29]
	v_lshlrev_b64 v[30:31], 8, v[30:31]
	v_lshl_add_u64 v[12:13], v[2:3], 0, v[12:13]
	v_lshl_add_u64 v[26:27], v[2:3], 0, v[26:27]
	global_load_dword v64, v[4:5], off nt
	global_load_dword v65, v[12:13], off nt
	global_load_dword v66, v[6:7], off nt
	global_load_dword v67, v[26:27], off nt
	v_lshl_add_u64 v[4:5], v[2:3], 0, v[8:9]
	v_lshlrev_b64 v[6:7], 8, v[0:1]
	v_lshl_add_u64 v[28:29], v[2:3], 0, v[28:29]
	v_lshl_add_u64 v[30:31], v[2:3], 0, v[30:31]
	v_lshl_add_u64 v[6:7], v[2:3], 0, v[6:7]
	global_load_dword v0, v[4:5], off nt
	global_load_dword v68, v[28:29], off nt
	global_load_dword v69, v[6:7], off nt
	global_load_dword v70, v[30:31], off nt
	s_add_i32 s8, s8, 16
	s_add_i32 s7, s7, 16
	s_add_i32 s4, s4, -16
	v_mad_u64_u32 v[4:5], s[10:11], v41, s26, v[18:19]
	s_cmp_lg_u32 s4, 0
	v_mad_u64_u32 v[6:7], s[10:11], v40, s26, v[18:19]
	v_mad_u64_u32 v[8:9], s[10:11], v43, s26, v[18:19]
	v_mad_u64_u32 v[10:11], s[10:11], v42, s26, v[18:19]
	v_mad_u64_u32 v[12:13], s[10:11], v45, s26, v[18:19]
	v_mad_u64_u32 v[26:27], s[10:11], v44, s26, v[18:19]
	v_mad_u64_u32 v[28:29], s[10:11], v47, s26, v[18:19]
	v_mad_u64_u32 v[30:31], s[10:11], v46, s26, v[18:19]
	v_mad_u64_u32 v[32:33], s[10:11], v49, s26, v[18:19]
	v_mad_u64_u32 v[34:35], s[10:11], v48, s26, v[18:19]
	v_mad_u64_u32 v[36:37], s[10:11], v51, s26, v[18:19]
	v_mad_u64_u32 v[40:41], s[10:11], v50, s26, v[18:19]
	v_mad_u64_u32 v[42:43], s[10:11], v53, s26, v[18:19]
	v_mad_u64_u32 v[44:45], s[10:11], v52, s26, v[18:19]
	v_mad_u64_u32 v[46:47], s[10:11], v55, s26, v[18:19]
	v_mad_u64_u32 v[48:49], s[10:11], v54, s26, v[18:19]
	s_waitcnt vmcnt(15)
	ds_write_b32 v4, v56
	s_waitcnt vmcnt(14)
	ds_write_b32 v6, v57
	s_waitcnt vmcnt(13)
	ds_write_b32 v8, v58
	s_waitcnt vmcnt(12)
	ds_write_b32 v10, v59
	s_waitcnt vmcnt(11)
	ds_write_b32 v12, v60
	s_waitcnt vmcnt(10)
	ds_write_b32 v26, v61
	s_waitcnt vmcnt(9)
	ds_write_b32 v28, v62
	s_waitcnt vmcnt(8)
	ds_write_b32 v30, v63
	s_waitcnt vmcnt(7)
	ds_write_b32 v32, v64
	s_waitcnt vmcnt(6)
	ds_write_b32 v34, v65
	s_waitcnt vmcnt(5)
	ds_write_b32 v36, v66
	s_waitcnt vmcnt(4)
	ds_write_b32 v40, v67
	s_waitcnt vmcnt(3)
	ds_write_b32 v42, v0
	s_waitcnt vmcnt(2)
	ds_write_b32 v44, v68
	s_waitcnt vmcnt(1)
	ds_write_b32 v46, v69
	s_waitcnt vmcnt(0)
	ds_write_b32 v48, v70
	s_cbranch_scc1 .LBB0_1460
; #define LAS __attribute__((address_space(3)))
; __device__ __forceinline__ v4u pack8(const float (&f)[8]) { v4u w; w.x = cvt_pk_bf16(f[0], f[1]); w.y = cvt_pk_bf16(f[2], f[3]); w.z = cvt_pk_bf16(f[4], f[5]); w.w = cvt_pk_bf16(f[6], f[7]); return w; }
; __device__ __forceinline__ void tr_item(const float* __restrict__ W, int ldw, int k0, int n0, bf16* __restrict__ WT, int ldt, int drow, const float* __restrict__ mu, LAS float* scr, int lane, const float* __restrict__ gs = nullptr) {
;     ...
;     if (mu) {
; #pragma unroll
;         for (int e = 0; e < 8; ++e) mv[e] = mu[k0 + 8 * c + e];
;     } else if (gs) {
; #pragma unroll
;         for (int e = 0; e < 8; ++e) mv[e] = gs[k0 + 8 * c + e];
;     }
; #pragma unroll
;     for (int j = 0; j < 4; ++j) {
;         const int n = (lane >> 3) + 8 * j; const LAS float* s = scr + (8 * c) * 33 + n;
;         float f[8];
; #pragma unroll
;         for (int e = 0; e < 8; ++e) f[e] = s[e * 33];
;         bf16* dp = WT + (size_t)(drow + n) * ldt + k0 + 8 * c;
;         if (mu) {
;             float f1[8], f2[8];
; #pragma unroll
;             for (int e = 0; e < 8; ++e) { f1[e] = f[e] * (1.f - mv[e]); f2[e] = f[e] * mv[e]; }
;             *(v4u*)dp = pack8(f1); *(v4u*)(dp + 1024) = pack8(f2);
;         } else { if (gs) {
; #pragma unroll
;             for (int e = 0; e < 8; ++e) f[e] *= mv[e]; }
;             *(v4u*)dp = pack8(f); }
;     }
; __device__ __forceinline__ void ph_p0(const Params& p, LAS unsigned char* lds, int tid, int lane, int wave) {
;     ...
;         if (r < C_W1) { const int j = r / 32, q = r % 32, kb = q / 2, nb = q % 2;
;             tr_item(p.in[I_W1] + (size_t)j * D * LW, LW, 64 * kb, 32 * nb, (bf16*)(ws + WS_WRW + j * SZ_WRW), KRW, 3072 + 32 * nb, p.in[I_MU] + (size_t)(j * 6 + 1) * D, scr, lane); continue; }
	s_mul_i32 s7, s94, 6
	s_mul_hi_u32 s4, s94, 0xe00000
	s_mul_i32 s5, s94, 0xe00000
	s_or_b32 s94, s7, 1
	s_add_u32 s7, s36, s5
	s_addc_u32 s8, s37, s4
	s_lshl_b64 s[4:5], s[94:95], 12
	s_or_b32 s1, s1, 0xc00
	s_add_u32 s4, s50, s4
	v_or_b32_e32 v0, s0, v20
	s_addc_u32 s5, s51, s5
	s_waitcnt lgkmcnt(0)
	v_lshlrev_b32_e32 v0, 2, v0
	global_load_dwordx4 v[2:5], v0, s[4:5]
	global_load_dwordx4 v[6:9], v0, s[4:5] offset:16
	ds_read2_b32 v[26:27], v19 offset0:33 offset1:41
	ds_read2_b32 v[28:29], v19 offset0:66 offset1:74
	ds_read2_b32 v[30:31], v19 offset0:99 offset1:107
	ds_read2_b32 v[32:33], v19 offset0:132 offset1:140
	ds_read2_b32 v[34:35], v19 offset0:165 offset1:173
	ds_read2_b32 v[36:37], v19 offset0:198 offset1:206
	ds_read2_b32 v[40:41], v19 offset0:231 offset1:239
	ds_read2_b32 v[42:43], v19 offset1:8
	s_lshl_b32 s0, s0, 1
	s_add_u32 s4, s7, s0
	v_lshlrev_b32_e32 v0, 1, v20
	v_or_b32_e32 v10, s1, v17
	s_addc_u32 s5, s8, 0
	v_or_b32_e32 v11, s1, v21
	v_lshl_add_u64 v[44:45], s[4:5], 0, v[0:1]
	v_lshlrev_b32_e32 v0, 12, v10
	v_lshl_add_u64 v[46:47], v[44:45], 0, v[0:1]
	v_lshlrev_b32_e32 v0, 12, v11
	v_lshl_add_u64 v[48:49], v[44:45], 0, v[0:1]
	s_waitcnt vmcnt(1)
	v_sub_f32_e32 v53, 1.0, v5
	v_sub_f32_e32 v50, 1.0, v2
	s_waitcnt lgkmcnt(0)
	v_mul_f32_e32 v0, v2, v42
	v_sub_f32_e32 v51, 1.0, v3
	v_mul_f32_e32 v10, v3, v26
	v_sub_f32_e32 v52, 1.0, v4
	v_mul_f32_e32 v11, v4, v28
	v_mul_f32_e32 v12, v5, v30
	s_waitcnt vmcnt(0)
	v_sub_f32_e32 v54, 1.0, v6
	v_mul_f32_e32 v13, v6, v32
	v_sub_f32_e32 v55, 1.0, v7
	v_mul_f32_e32 v56, v7, v34
	v_sub_f32_e32 v57, 1.0, v8
	v_sub_f32_e32 v59, 1.0, v9
	v_mul_f32_e32 v30, v53, v30
	v_mul_f32_e32 v58, v8, v36
	v_mul_f32_e32 v60, v9, v40
	v_mul_f32_e32 v61, v2, v43
	v_mul_f32_e32 v62, v3, v27
	v_mul_f32_e32 v63, v4, v29
	v_mul_f32_e32 v64, v5, v31
	v_mul_f32_e32 v42, v50, v42
	v_mul_f32_e32 v69, v51, v26
	v_mul_f32_e32 v70, v52, v28
	v_mul_f32_e32 v32, v54, v32
	v_mul_f32_e32 v34, v55, v34
	v_mul_f32_e32 v36, v57, v36
	v_mul_f32_e32 v40, v59, v40
	v_cvt_pk_bf16_f32 v10, v0, v10
	v_cvt_pk_bf16_f32 v11, v11, v12
	v_cvt_pk_bf16_f32 v12, v13, v56
	v_cvt_pk_bf16_f32 v13, v58, v60
	v_mul_f32_e32 v0, v50, v43
	v_mul_f32_e32 v27, v51, v27
	v_mul_f32_e32 v43, v52, v29
	v_mul_f32_e32 v56, v53, v31
	v_cvt_pk_bf16_f32 v28, v42, v69
	v_cvt_pk_bf16_f32 v29, v70, v30
	v_cvt_pk_bf16_f32 v30, v32, v34
	v_cvt_pk_bf16_f32 v31, v36, v40
	v_mul_f32_e32 v65, v6, v33
	v_mul_f32_e32 v66, v7, v35
	v_mul_f32_e32 v67, v8, v37
	v_mul_f32_e32 v68, v9, v41
	v_mul_f32_e32 v33, v54, v33
	v_mul_f32_e32 v35, v55, v35
	v_mul_f32_e32 v37, v57, v37
	v_mul_f32_e32 v41, v59, v41
	v_cvt_pk_bf16_f32 v26, v61, v62
	global_store_dwordx4 v[46:47], v[10:13], off offset:2048
	s_nop 1
	v_cvt_pk_bf16_f32 v10, v0, v27
	v_cvt_pk_bf16_f32 v11, v43, v56
	v_cvt_pk_bf16_f32 v12, v33, v35
	v_cvt_pk_bf16_f32 v13, v37, v41
	global_store_dwordx4 v[46:47], v[28:31], off
	global_store_dwordx4 v[48:49], v[10:13], off
	v_cvt_pk_bf16_f32 v27, v63, v64
	v_or_b32_e32 v0, s1, v38
	v_cvt_pk_bf16_f32 v28, v65, v66
	v_cvt_pk_bf16_f32 v29, v67, v68
	global_store_dwordx4 v[48:49], v[26:29], off offset:2048
	ds_read2_b32 v[26:27], v19 offset0:16 offset1:24
	ds_read2_b32 v[28:29], v19 offset0:49 offset1:57
	ds_read2_b32 v[30:31], v19 offset0:82 offset1:90
	ds_read2_b32 v[32:33], v19 offset0:115 offset1:123
	ds_read2_b32 v[34:35], v19 offset0:148 offset1:156
	ds_read2_b32 v[36:37], v19 offset0:181 offset1:189
	ds_read2_b32 v[40:41], v19 offset0:214 offset1:222
	ds_read2_b32 v[42:43], v19 offset0:247 offset1:255
	v_lshlrev_b32_e32 v0, 12, v0
	v_lshl_add_u64 v[46:47], v[44:45], 0, v[0:1]
	s_waitcnt lgkmcnt(7)
	v_mul_f32_e32 v0, v50, v26
	s_waitcnt lgkmcnt(6)
	v_mul_f32_e32 v10, v51, v28
	s_waitcnt lgkmcnt(5)
	v_mul_f32_e32 v11, v52, v30
	s_waitcnt lgkmcnt(4)
	v_mul_f32_e32 v12, v53, v32
	s_waitcnt lgkmcnt(3)
	v_mul_f32_e32 v13, v54, v34
	s_waitcnt lgkmcnt(2)
	v_mul_f32_e32 v48, v55, v36
	s_waitcnt lgkmcnt(1)
	v_mul_f32_e32 v49, v57, v40
	s_waitcnt lgkmcnt(0)
	v_mul_f32_e32 v56, v59, v42
	v_cvt_pk_bf16_f32 v10, v0, v10
	v_cvt_pk_bf16_f32 v11, v11, v12
	v_cvt_pk_bf16_f32 v12, v13, v48
	v_cvt_pk_bf16_f32 v13, v49, v56
	v_or_b32_e32 v0, s1, v39
	v_mul_f32_e32 v26, v2, v26
	v_mul_f32_e32 v28, v3, v28
	v_mul_f32_e32 v30, v4, v30
	v_mul_f32_e32 v32, v5, v32
	v_mul_f32_e32 v34, v6, v34
	v_mul_f32_e32 v36, v7, v36
	v_mul_f32_e32 v40, v8, v40
	v_mul_f32_e32 v42, v9, v42
	global_store_dwordx4 v[46:47], v[10:13], off
	v_lshlrev_b32_e32 v0, 12, v0
	v_mul_f32_e32 v6, v6, v35
	v_cvt_pk_bf16_f32 v10, v26, v28
	v_cvt_pk_bf16_f32 v11, v30, v32
	v_cvt_pk_bf16_f32 v12, v34, v36
	v_cvt_pk_bf16_f32 v13, v40, v42
	global_store_dwordx4 v[46:47], v[10:13], off offset:2048
	v_mul_f32_e32 v26, v4, v31
	v_mul_f32_e32 v4, v53, v33
	v_lshl_add_u64 v[10:11], v[44:45], 0, v[0:1]
	v_mul_f32_e32 v0, v50, v27
	v_mul_f32_e32 v12, v2, v27
	v_mul_f32_e32 v2, v51, v29
	v_mul_f32_e32 v13, v3, v29
	v_mul_f32_e32 v3, v52, v31
	v_mul_f32_e32 v27, v5, v33
	v_mul_f32_e32 v5, v54, v35
	v_mul_f32_e32 v28, v55, v37
	v_mul_f32_e32 v29, v57, v41
	v_mul_f32_e32 v30, v59, v43
	v_cvt_pk_bf16_f32 v2, v0, v2
	v_cvt_pk_bf16_f32 v3, v3, v4
	v_cvt_pk_bf16_f32 v4, v5, v28
	v_cvt_pk_bf16_f32 v5, v29, v30
	v_mul_f32_e32 v7, v7, v37
	v_mul_f32_e32 v8, v8, v41
	v_mul_f32_e32 v9, v9, v43
	global_store_dwordx4 v[10:11], v[2:5], off
	s_nop 1
	v_cvt_pk_bf16_f32 v2, v12, v13
	v_cvt_pk_bf16_f32 v3, v26, v27
	v_cvt_pk_bf16_f32 v4, v6, v7
	v_cvt_pk_bf16_f32 v5, v8, v9
	global_store_dwordx4 v[10:11], v[2:5], off offset:2048
	s_waitcnt lgkmcnt(0)

; __device__ __forceinline__ void tr_item(const float* __restrict__ W, int ldw, int k0, int n0, bf16* __restrict__ WT, int ldt, int drow, const float* __restrict__ mu, LAS float* scr, int lane, const float* __restrict__ gs = nullptr) {
; #pragma unroll 8
;     for (int i = 0; i < 32; ++i) { const int kk = 2 * i + (lane >> 5); scr[kk * 33 + (lane & 31)] = W[(size_t)(k0 + kk) * ldw + n0 + (lane & 31)]; }
;     asm volatile("s_waitcnt lgkmcnt(0)" ::: "memory");
.LBB0_1486:
	s_lshl_b32 s9, s4, 1
	s_lshl_b32 s10, s7, 1
	v_or_b32_e32 v41, s10, v14
	s_add_i32 s11, s9, 4
	s_add_i32 s12, s10, 4
	s_add_i32 s14, s10, 8
	v_add_u32_e32 v0, s1, v41
	v_or_b32_e32 v42, s11, v15
	v_or_b32_e32 v43, s12, v14
	v_mov_b32_e32 v7, v1
	v_or_b32_e32 v40, s9, v15
	s_add_i32 s16, s10, 12
	v_or_b32_e32 v45, s14, v14
	s_waitcnt lgkmcnt(3)
	v_lshlrev_b64 v[32:33], 12, v[0:1]
	v_add_u32_e32 v6, s5, v42
	v_add_u32_e32 v0, s1, v43
	v_mov_b32_e32 v5, v1
	s_add_i32 s13, s9, 8
	s_add_i32 s15, s9, 12
	s_add_i32 s18, s10, 16
	v_add_u32_e32 v4, s5, v40
	v_or_b32_e32 v47, s16, v14
	v_lshlrev_b64 v[6:7], 12, v[6:7]
	v_lshlrev_b64 v[34:35], 12, v[0:1]
	v_add_u32_e32 v0, s1, v45
	s_add_i32 s20, s10, 20
	v_or_b32_e32 v44, s13, v15
	v_or_b32_e32 v46, s15, v15
	v_or_b32_e32 v49, s18, v14
	v_lshlrev_b64 v[4:5], 12, v[4:5]
	v_lshl_add_u64 v[32:33], v[2:3], 0, v[32:33]
	v_lshl_add_u64 v[6:7], v[2:3], 0, v[6:7]
	v_lshlrev_b64 v[36:37], 12, v[0:1]
	v_add_u32_e32 v0, s1, v47
	v_mov_b32_e32 v9, v1
	v_mov_b32_e32 v11, v1
	s_add_i32 s17, s9, 16
	s_add_i32 s19, s9, 20
	s_add_i32 s22, s10, 24
	v_or_b32_e32 v51, s20, v14
	v_add_u32_e32 v8, s5, v44
	v_add_u32_e32 v10, s5, v46
	v_lshl_add_u64 v[4:5], v[2:3], 0, v[4:5]
	v_lshl_add_u64 v[34:35], v[2:3], 0, v[34:35]
	global_load_dword v56, v[32:33], off nt
	global_load_dword v57, v[4:5], off nt
	global_load_dword v58, v[34:35], off nt
	global_load_dword v59, v[6:7], off nt
	v_lshlrev_b64 v[6:7], 12, v[0:1]
	v_add_u32_e32 v0, s1, v49
	s_add_i32 s21, s9, 24
	s_add_i32 s9, s9, 28
	s_add_i32 s10, s10, 28
	v_or_b32_e32 v48, s17, v15
	v_or_b32_e32 v50, s19, v15
	v_or_b32_e32 v53, s22, v14
	v_lshlrev_b64 v[8:9], 12, v[8:9]
	v_lshlrev_b64 v[10:11], 12, v[10:11]
	v_lshl_add_u64 v[4:5], v[2:3], 0, v[36:37]
	v_lshl_add_u64 v[6:7], v[2:3], 0, v[6:7]
	v_lshlrev_b64 v[32:33], 12, v[0:1]
	v_add_u32_e32 v0, s1, v51
	s_waitcnt lgkmcnt(0)
	v_mov_b32_e32 v13, v1
	v_mov_b32_e32 v27, v1
	v_or_b32_e32 v52, s21, v15
	v_or_b32_e32 v54, s9, v15
	v_or_b32_e32 v55, s10, v14
	v_add_u32_e32 v12, s5, v48
	v_add_u32_e32 v26, s5, v50
	v_lshl_add_u64 v[8:9], v[2:3], 0, v[8:9]
	v_lshl_add_u64 v[10:11], v[2:3], 0, v[10:11]
	global_load_dword v60, v[4:5], off nt
	global_load_dword v61, v[8:9], off nt
	global_load_dword v62, v[6:7], off nt
	global_load_dword v63, v[10:11], off nt
	v_lshlrev_b64 v[6:7], 12, v[0:1]
	v_add_u32_e32 v0, s1, v53
	v_mov_b32_e32 v29, v1
	v_mov_b32_e32 v31, v1
	v_add_u32_e32 v28, s5, v52
	v_add_u32_e32 v30, s5, v54
	v_lshlrev_b64 v[12:13], 12, v[12:13]
	v_lshlrev_b64 v[26:27], 12, v[26:27]
	v_lshl_add_u64 v[4:5], v[2:3], 0, v[32:33]
	v_lshl_add_u64 v[6:7], v[2:3], 0, v[6:7]
	v_lshlrev_b64 v[8:9], 12, v[0:1]
	v_add_u32_e32 v0, s1, v55
	v_lshlrev_b64 v[28:29], 12, v[28:29]
	v_lshlrev_b64 v[30:31], 12, v[30:31]
	v_lshl_add_u64 v[12:13], v[2:3], 0, v[12:13]
	v_lshl_add_u64 v[26:27], v[2:3], 0, v[26:27]
	global_load_dword v64, v[4:5], off nt
	global_load_dword v65, v[12:13], off nt
	global_load_dword v66, v[6:7], off nt
	global_load_dword v67, v[26:27], off nt
	v_lshl_add_u64 v[4:5], v[2:3], 0, v[8:9]
	v_lshlrev_b64 v[6:7], 12, v[0:1]
	v_lshl_add_u64 v[28:29], v[2:3], 0, v[28:29]
	v_lshl_add_u64 v[30:31], v[2:3], 0, v[30:31]
	v_lshl_add_u64 v[6:7], v[2:3], 0, v[6:7]
	global_load_dword v0, v[4:5], off nt
	global_load_dword v68, v[28:29], off nt
	global_load_dword v69, v[6:7], off nt
	global_load_dword v70, v[30:31], off nt
	s_add_i32 s7, s7, 16
	s_add_i32 s4, s4, 16
	s_add_i32 s8, s8, -16
	v_mad_u64_u32 v[4:5], s[10:11], v41, s26, v[18:19]
	s_cmp_lg_u32 s8, 0
	v_mad_u64_u32 v[6:7], s[10:11], v40, s26, v[18:19]
	v_mad_u64_u32 v[8:9], s[10:11], v43, s26, v[18:19]
	v_mad_u64_u32 v[10:11], s[10:11], v42, s26, v[18:19]
	v_mad_u64_u32 v[12:13], s[10:11], v45, s26, v[18:19]
	v_mad_u64_u32 v[26:27], s[10:11], v44, s26, v[18:19]
	v_mad_u64_u32 v[28:29], s[10:11], v47, s26, v[18:19]
	v_mad_u64_u32 v[30:31], s[10:11], v46, s26, v[18:19]
	v_mad_u64_u32 v[32:33], s[10:11], v49, s26, v[18:19]
	v_mad_u64_u32 v[34:35], s[10:11], v48, s26, v[18:19]
	v_mad_u64_u32 v[36:37], s[10:11], v51, s26, v[18:19]
	v_mad_u64_u32 v[40:41], s[10:11], v50, s26, v[18:19]
	v_mad_u64_u32 v[42:43], s[10:11], v53, s26, v[18:19]
	v_mad_u64_u32 v[44:45], s[10:11], v52, s26, v[18:19]
	v_mad_u64_u32 v[46:47], s[10:11], v55, s26, v[18:19]
	v_mad_u64_u32 v[48:49], s[10:11], v54, s26, v[18:19]
	s_waitcnt vmcnt(15)
	ds_write_b32 v4, v56
	s_waitcnt vmcnt(14)
	ds_write_b32 v6, v57
	s_waitcnt vmcnt(13)
	ds_write_b32 v8, v58
	s_waitcnt vmcnt(12)
	ds_write_b32 v10, v59
	s_waitcnt vmcnt(11)
	ds_write_b32 v12, v60
	s_waitcnt vmcnt(10)
	ds_write_b32 v26, v61
	s_waitcnt vmcnt(9)
	ds_write_b32 v28, v62
	s_waitcnt vmcnt(8)
	ds_write_b32 v30, v63
	s_waitcnt vmcnt(7)
	ds_write_b32 v32, v64
	s_waitcnt vmcnt(6)
	ds_write_b32 v34, v65
	s_waitcnt vmcnt(5)
	ds_write_b32 v36, v66
	s_waitcnt vmcnt(4)
	ds_write_b32 v40, v67
	s_waitcnt vmcnt(3)
	ds_write_b32 v42, v0
	s_waitcnt vmcnt(2)
	ds_write_b32 v44, v68
	s_waitcnt vmcnt(1)
	ds_write_b32 v46, v69
	s_waitcnt vmcnt(0)
	ds_write_b32 v48, v70
	s_cbranch_scc1 .LBB0_1486
; #define LAS __attribute__((address_space(3)))
; __device__ __forceinline__ v4u pack8(const float (&f)[8]) { v4u w; w.x = cvt_pk_bf16(f[0], f[1]); w.y = cvt_pk_bf16(f[2], f[3]); w.z = cvt_pk_bf16(f[4], f[5]); w.w = cvt_pk_bf16(f[6], f[7]); return w; }
; __device__ __forceinline__ void tr_item(const float* __restrict__ W, int ldw, int k0, int n0, bf16* __restrict__ WT, int ldt, int drow, const float* __restrict__ mu, LAS float* scr, int lane, const float* __restrict__ gs = nullptr) {
;     ...
;     for (int j = 0; j < 4; ++j) {
;         const int n = (lane >> 3) + 8 * j; const LAS float* s = scr + (8 * c) * 33 + n;
;         float f[8];
; #pragma unroll
;         for (int e = 0; e < 8; ++e) f[e] = s[e * 33];
;         bf16* dp = WT + (size_t)(drow + n) * ldt + k0 + 8 * c;
;         if (mu) {
;             float f1[8], f2[8];
; #pragma unroll
;             for (int e = 0; e < 8; ++e) { f1[e] = f[e] * (1.f - mv[e]); f2[e] = f[e] * mv[e]; }
;             *(v4u*)dp = pack8(f1); *(v4u*)(dp + 1024) = pack8(f2);
;         } else { if (gs) {
; #pragma unroll
;             for (int e = 0; e < 8; ++e) f[e] *= mv[e]; }
;             *(v4u*)dp = pack8(f); }
;     }
; __device__ __forceinline__ void ph_p0(const Params& p, LAS unsigned char* lds, int tid, int lane, int wave) {
;     ...
;         if (r < C_WOUT) { const int j = r / 1024, q = r % 1024, kb = q / 32, nb = q % 32;
;             tr_item(p.in[I_RWOUT] + (size_t)j * RV * D, D, 64 * kb, 32 * nb, (bf16*)(ws + WS_WOUT + j * SZ_WOUT), RV, 32 * nb, nullptr, scr, lane); continue; }
	s_lshl_b64 s[4:5], s[94:95], 22
	v_readlane_b32 s7, v252, 20
	s_add_u32 s4, s7, s4
	v_readlane_b32 s7, v252, 21
	s_addc_u32 s5, s7, s5
	s_lshl_b32 s1, s1, 1
	s_waitcnt lgkmcnt(0)
	s_add_u32 s4, s4, s1
	s_addc_u32 s5, s5, 0
	v_lshlrev_b32_e32 v0, 1, v20
	ds_read2_b32 v[8:9], v19 offset0:33 offset1:41
	ds_read2_b32 v[10:11], v19 offset1:8
	ds_read2_b32 v[12:13], v19 offset0:66 offset1:74
	ds_read2_b32 v[26:27], v19 offset0:99 offset1:107
	ds_read2_b32 v[28:29], v19 offset0:132 offset1:140
	ds_read2_b32 v[30:31], v19 offset0:165 offset1:173
	ds_read2_b32 v[32:33], v19 offset0:198 offset1:206
	ds_read2_b32 v[34:35], v19 offset0:231 offset1:239
	v_lshl_add_u64 v[6:7], s[4:5], 0, v[0:1]
	v_or_b32_e32 v0, s0, v17
	v_lshlrev_b32_e32 v0, 12, v0
	v_lshl_add_u64 v[36:37], v[6:7], 0, v[0:1]
	v_or_b32_e32 v0, s0, v21
	v_lshlrev_b32_e32 v0, 12, v0
	s_waitcnt lgkmcnt(6)
	v_cvt_pk_bf16_f32 v2, v10, v8
	s_waitcnt lgkmcnt(4)
	v_cvt_pk_bf16_f32 v3, v12, v26
	s_waitcnt lgkmcnt(2)
	v_cvt_pk_bf16_f32 v4, v28, v30
	s_waitcnt lgkmcnt(0)
	v_cvt_pk_bf16_f32 v5, v32, v34
	global_store_dwordx4 v[36:37], v[2:5], off
	v_lshl_add_u64 v[36:37], v[6:7], 0, v[0:1]
	v_or_b32_e32 v0, s0, v38
	v_cvt_pk_bf16_f32 v2, v11, v9
	v_cvt_pk_bf16_f32 v3, v13, v27
	v_cvt_pk_bf16_f32 v4, v29, v31
	v_cvt_pk_bf16_f32 v5, v33, v35
	global_store_dwordx4 v[36:37], v[2:5], off
	ds_read2_b32 v[8:9], v19 offset0:16 offset1:24
	ds_read2_b32 v[10:11], v19 offset0:49 offset1:57
	ds_read2_b32 v[12:13], v19 offset0:82 offset1:90
	ds_read2_b32 v[26:27], v19 offset0:115 offset1:123
	ds_read2_b32 v[28:29], v19 offset0:148 offset1:156
	ds_read2_b32 v[30:31], v19 offset0:181 offset1:189
	ds_read2_b32 v[32:33], v19 offset0:214 offset1:222
	ds_read2_b32 v[34:35], v19 offset0:247 offset1:255
	v_lshlrev_b32_e32 v0, 12, v0
	v_lshl_add_u64 v[36:37], v[6:7], 0, v[0:1]
	v_or_b32_e32 v0, s0, v39
	v_lshlrev_b32_e32 v0, 12, v0
	s_waitcnt lgkmcnt(6)
	v_cvt_pk_bf16_f32 v2, v8, v10
	s_waitcnt lgkmcnt(4)
	v_cvt_pk_bf16_f32 v3, v12, v26
	s_waitcnt lgkmcnt(2)
	v_cvt_pk_bf16_f32 v4, v28, v30
	s_waitcnt lgkmcnt(0)
	v_cvt_pk_bf16_f32 v5, v32, v34
	v_lshl_add_u64 v[6:7], v[6:7], 0, v[0:1]
	global_store_dwordx4 v[36:37], v[2:5], off
	s_nop 1
	v_cvt_pk_bf16_f32 v2, v9, v11
	v_cvt_pk_bf16_f32 v3, v13, v27
	v_cvt_pk_bf16_f32 v4, v29, v31
	v_cvt_pk_bf16_f32 v5, v33, v35
	global_store_dwordx4 v[6:7], v[2:5], off
	s_waitcnt lgkmcnt(0)
